# K-loops: closing barrier of each MFMA block moved 4 MFMAs up (tail MFMAs overlap the partner's block start), on top of prio-before-barrier + P0 item pipeline
# baseline (speedup 1.0000x reference)
.LBB0_446:
	ds_read_b128 v[148:151], v165
	ds_read_b128 v[174:177], v165 offset:1024
	ds_read_b128 v[180:183], v165 offset:2048
	ds_read_b128 v[184:187], v165 offset:3072
	ds_read_b128 v[188:191], v169
	ds_read_b128 v[192:195], v169 offset:1024
	ds_read_b128 v[196:199], v169 offset:2048
	ds_read_b128 v[200:203], v169 offset:3072
	s_add_u32 s50, s4, 0xfff00080
	s_addc_u32 s51, s5, -1
	s_cmp_eq_u32 s68, 60
	s_cselect_b32 s53, s3, s51
	s_cselect_b32 s52, s8, s50
	s_cselect_b32 s51, s39, s65
	s_cselect_b32 s50, s45, s63
	v_lshl_add_u64 v[154:155], s[4:5], 0, v[140:141]
	s_add_i32 m0, s7, 0xc000
	ds_read_b128 v[204:207], v173
	ds_read_b128 v[208:211], v173 offset:1024
	ds_read_b128 v[212:215], v173 offset:2048
	ds_read_b128 v[216:219], v173 offset:3072
	ds_read_b128 v[220:223], v173 offset:4096
	ds_read_b128 v[224:227], v173 offset:5120
	ds_read_b128 v[228:231], v173 offset:6144
	ds_read_b128 v[236:239], v173 offset:7168
	global_load_lds_dwordx4 v[154:155], off
	v_lshl_add_u64 v[154:155], s[4:5], 0, v[142:143]
	s_add_i32 m0, s7, 0xe000
	s_nop 0
	global_load_lds_dwordx4 v[154:155], off
	s_waitcnt vmcnt(8)
	s_waitcnt lgkmcnt(0)
	s_setprio 1
	s_barrier
	v_mfma_f32_16x16x32_bf16 v[126:129], v[148:151], v[204:207], v[126:129]
	v_mfma_f32_16x16x32_bf16 v[122:125], v[180:183], v[204:207], v[122:125]
	v_mfma_f32_16x16x32_bf16 v[110:113], v[148:151], v[212:215], v[110:113]
	v_mfma_f32_16x16x32_bf16 v[106:109], v[180:183], v[212:215], v[106:109]
	v_mfma_f32_16x16x32_bf16 v[94:97], v[148:151], v[220:223], v[94:97]
	v_mfma_f32_16x16x32_bf16 v[90:93], v[180:183], v[220:223], v[90:93]
	v_mfma_f32_16x16x32_bf16 v[78:81], v[148:151], v[228:231], v[78:81]
	v_mfma_f32_16x16x32_bf16 v[74:77], v[180:183], v[228:231], v[74:77]
	v_mfma_f32_16x16x32_bf16 v[126:129], v[174:177], v[208:211], v[126:129]
	v_mfma_f32_16x16x32_bf16 v[122:125], v[184:187], v[208:211], v[122:125]
	v_mfma_f32_16x16x32_bf16 v[110:113], v[174:177], v[216:219], v[110:113]
	v_mfma_f32_16x16x32_bf16 v[106:109], v[184:187], v[216:219], v[106:109]
	v_mfma_f32_16x16x32_bf16 v[94:97], v[174:177], v[224:227], v[94:97]
	v_mfma_f32_16x16x32_bf16 v[90:93], v[184:187], v[224:227], v[90:93]
	v_mfma_f32_16x16x32_bf16 v[78:81], v[174:177], v[236:239], v[78:81]
	v_mfma_f32_16x16x32_bf16 v[74:77], v[184:187], v[236:239], v[74:77]
	v_mfma_f32_16x16x32_bf16 v[118:121], v[188:191], v[204:207], v[118:121]
	v_mfma_f32_16x16x32_bf16 v[114:117], v[196:199], v[204:207], v[114:117]
	v_mfma_f32_16x16x32_bf16 v[102:105], v[188:191], v[212:215], v[102:105]
	v_mfma_f32_16x16x32_bf16 v[98:101], v[196:199], v[212:215], v[98:101]
	v_mfma_f32_16x16x32_bf16 v[86:89], v[188:191], v[220:223], v[86:89]
	v_mfma_f32_16x16x32_bf16 v[82:85], v[196:199], v[220:223], v[82:85]
	v_mfma_f32_16x16x32_bf16 v[70:73], v[188:191], v[228:231], v[70:73]
	v_mfma_f32_16x16x32_bf16 v[66:69], v[196:199], v[228:231], v[66:69]
	v_mfma_f32_16x16x32_bf16 v[118:121], v[192:195], v[208:211], v[118:121]
	v_mfma_f32_16x16x32_bf16 v[114:117], v[200:203], v[208:211], v[114:117]
	v_mfma_f32_16x16x32_bf16 v[102:105], v[192:195], v[216:219], v[102:105]
	v_mfma_f32_16x16x32_bf16 v[98:101], v[200:203], v[216:219], v[98:101]
	s_barrier
	v_mfma_f32_16x16x32_bf16 v[86:89], v[192:195], v[224:227], v[86:89]
	v_mfma_f32_16x16x32_bf16 v[82:85], v[200:203], v[224:227], v[82:85]
	v_mfma_f32_16x16x32_bf16 v[70:73], v[192:195], v[236:239], v[70:73]
	v_mfma_f32_16x16x32_bf16 v[66:69], v[200:203], v[236:239], v[66:69]
	s_setprio 0
	s_add_i32 s69, s59, s35
	v_lshl_add_u64 v[154:155], s[50:51], 0, v[132:133]
	s_mov_b32 m0, s69
	ds_read_b128 v[204:207], v173 offset:16384
	ds_read_b128 v[208:211], v173 offset:17408
	ds_read_b128 v[212:215], v173 offset:18432
	ds_read_b128 v[216:219], v173 offset:19456
	ds_read_b128 v[220:223], v173 offset:20480
	ds_read_b128 v[224:227], v173 offset:21504
	ds_read_b128 v[228:231], v173 offset:22528
	ds_read_b128 v[236:239], v173 offset:23552
	global_load_lds_dwordx4 v[154:155], off
	s_add_i32 m0, s69, 0x2000
	s_add_u32 s70, s50, 0x100000
	v_lshl_add_u64 v[158:159], s[50:51], 0, v[136:137]
	s_addc_u32 s71, s51, 0
	s_add_i32 s69, s60, s35
	global_load_lds_dwordx4 v[158:159], off
	v_lshl_add_u64 v[162:163], s[70:71], 0, v[132:133]
	s_mov_b32 m0, s69
	v_lshl_add_u64 v[166:167], s[52:53], 0, v[134:135]
	global_load_lds_dwordx4 v[162:163], off
	v_lshl_add_u64 v[162:163], s[70:71], 0, v[136:137]
	s_add_i32 m0, s69, 0x2000
	s_nop 0
	global_load_lds_dwordx4 v[162:163], off
	v_lshl_add_u64 v[162:163], s[52:53], 0, v[130:131]
	s_mov_b32 m0, s7
	s_nop 0
	global_load_lds_dwordx4 v[162:163], off
	s_mov_b32 m0, s37
	s_nop 0
	global_load_lds_dwordx4 v[166:167], off
	s_waitcnt vmcnt(8)
	s_waitcnt lgkmcnt(0)
	s_setprio 1
	s_barrier
	v_mfma_f32_16x16x32_bf16 v[62:65], v[148:151], v[204:207], v[62:65]
	v_mfma_f32_16x16x32_bf16 v[58:61], v[180:183], v[204:207], v[58:61]
	v_mfma_f32_16x16x32_bf16 v[46:49], v[148:151], v[212:215], v[46:49]
	v_mfma_f32_16x16x32_bf16 v[42:45], v[180:183], v[212:215], v[42:45]
	v_mfma_f32_16x16x32_bf16 v[30:33], v[148:151], v[220:223], v[30:33]
	v_mfma_f32_16x16x32_bf16 v[26:29], v[180:183], v[220:223], v[26:29]
	v_mfma_f32_16x16x32_bf16 v[14:17], v[148:151], v[228:231], v[14:17]
	v_mfma_f32_16x16x32_bf16 v[10:13], v[180:183], v[228:231], v[10:13]
	v_mfma_f32_16x16x32_bf16 v[62:65], v[174:177], v[208:211], v[62:65]
	v_mfma_f32_16x16x32_bf16 v[58:61], v[184:187], v[208:211], v[58:61]
	v_mfma_f32_16x16x32_bf16 v[46:49], v[174:177], v[216:219], v[46:49]
	v_mfma_f32_16x16x32_bf16 v[42:45], v[184:187], v[216:219], v[42:45]
	v_mfma_f32_16x16x32_bf16 v[30:33], v[174:177], v[224:227], v[30:33]
	v_mfma_f32_16x16x32_bf16 v[26:29], v[184:187], v[224:227], v[26:29]
	v_mfma_f32_16x16x32_bf16 v[14:17], v[174:177], v[236:239], v[14:17]
	v_mfma_f32_16x16x32_bf16 v[10:13], v[184:187], v[236:239], v[10:13]
	v_mfma_f32_16x16x32_bf16 v[54:57], v[188:191], v[204:207], v[54:57]
	v_mfma_f32_16x16x32_bf16 v[50:53], v[196:199], v[204:207], v[50:53]
	v_mfma_f32_16x16x32_bf16 v[38:41], v[188:191], v[212:215], v[38:41]
	v_mfma_f32_16x16x32_bf16 v[34:37], v[196:199], v[212:215], v[34:37]
	v_mfma_f32_16x16x32_bf16 v[22:25], v[188:191], v[220:223], v[22:25]
	v_mfma_f32_16x16x32_bf16 v[18:21], v[196:199], v[220:223], v[18:21]
	v_mfma_f32_16x16x32_bf16 v[6:9], v[188:191], v[228:231], v[6:9]
	v_mfma_f32_16x16x32_bf16 v[2:5], v[196:199], v[228:231], v[2:5]
	v_mfma_f32_16x16x32_bf16 v[54:57], v[192:195], v[208:211], v[54:57]
	v_mfma_f32_16x16x32_bf16 v[50:53], v[200:203], v[208:211], v[50:53]
	v_mfma_f32_16x16x32_bf16 v[38:41], v[192:195], v[216:219], v[38:41]
	v_mfma_f32_16x16x32_bf16 v[34:37], v[200:203], v[216:219], v[34:37]
	s_barrier
	v_mfma_f32_16x16x32_bf16 v[22:25], v[192:195], v[224:227], v[22:25]
	v_mfma_f32_16x16x32_bf16 v[18:21], v[200:203], v[224:227], v[18:21]
	v_mfma_f32_16x16x32_bf16 v[6:9], v[192:195], v[236:239], v[6:9]
	v_mfma_f32_16x16x32_bf16 v[2:5], v[200:203], v[236:239], v[2:5]
	s_setprio 0
	s_add_i32 s69, 0, 0x18000
	v_add_u32_e32 v139, s69, v161
	s_add_i32 s70, 0, 0x1c000
	ds_read_b128 v[148:151], v139
	ds_read_b128 v[174:177], v139 offset:1024
	ds_read_b128 v[180:183], v139 offset:2048
	ds_read_b128 v[184:187], v139 offset:3072
	v_add_u32_e32 v139, s70, v161
	ds_read_b128 v[188:191], v139
	ds_read_b128 v[192:195], v139 offset:1024
	ds_read_b128 v[196:199], v139 offset:2048
	ds_read_b128 v[200:203], v139 offset:3072
	s_add_u32 s52, s52, 0x100000
	s_addc_u32 s53, s53, 0
	s_mov_b32 m0, s41
	v_lshl_add_u64 v[170:171], s[52:53], 0, v[130:131]
	ds_read_b128 v[204:207], v173 offset:32768
	ds_read_b128 v[208:211], v173 offset:33792
	ds_read_b128 v[212:215], v173 offset:34816
	ds_read_b128 v[216:219], v173 offset:35840
	ds_read_b128 v[220:223], v173 offset:36864
	ds_read_b128 v[224:227], v173 offset:37888
	ds_read_b128 v[228:231], v173 offset:38912
	ds_read_b128 v[236:239], v173 offset:39936
	global_load_lds_dwordx4 v[170:171], off
	v_lshl_add_u64 v[170:171], s[52:53], 0, v[134:135]
	s_mov_b32 m0, s43
	s_nop 0
	global_load_lds_dwordx4 v[170:171], off
	s_waitcnt vmcnt(8)
	s_waitcnt lgkmcnt(0)
	s_setprio 1
	s_barrier
	v_mfma_f32_16x16x32_bf16 v[126:129], v[148:151], v[204:207], v[126:129]
	v_mfma_f32_16x16x32_bf16 v[122:125], v[180:183], v[204:207], v[122:125]
	v_mfma_f32_16x16x32_bf16 v[110:113], v[148:151], v[212:215], v[110:113]
	v_mfma_f32_16x16x32_bf16 v[106:109], v[180:183], v[212:215], v[106:109]
	v_mfma_f32_16x16x32_bf16 v[94:97], v[148:151], v[220:223], v[94:97]
	v_mfma_f32_16x16x32_bf16 v[90:93], v[180:183], v[220:223], v[90:93]
	v_mfma_f32_16x16x32_bf16 v[78:81], v[148:151], v[228:231], v[78:81]
	v_mfma_f32_16x16x32_bf16 v[74:77], v[180:183], v[228:231], v[74:77]
	v_mfma_f32_16x16x32_bf16 v[126:129], v[174:177], v[208:211], v[126:129]
	v_mfma_f32_16x16x32_bf16 v[122:125], v[184:187], v[208:211], v[122:125]
	v_mfma_f32_16x16x32_bf16 v[110:113], v[174:177], v[216:219], v[110:113]
	v_mfma_f32_16x16x32_bf16 v[106:109], v[184:187], v[216:219], v[106:109]
	v_mfma_f32_16x16x32_bf16 v[94:97], v[174:177], v[224:227], v[94:97]
	v_mfma_f32_16x16x32_bf16 v[90:93], v[184:187], v[224:227], v[90:93]
	v_mfma_f32_16x16x32_bf16 v[78:81], v[174:177], v[236:239], v[78:81]
	v_mfma_f32_16x16x32_bf16 v[74:77], v[184:187], v[236:239], v[74:77]
	v_mfma_f32_16x16x32_bf16 v[118:121], v[188:191], v[204:207], v[118:121]
	v_mfma_f32_16x16x32_bf16 v[114:117], v[196:199], v[204:207], v[114:117]
	v_mfma_f32_16x16x32_bf16 v[102:105], v[188:191], v[212:215], v[102:105]
	v_mfma_f32_16x16x32_bf16 v[98:101], v[196:199], v[212:215], v[98:101]
	v_mfma_f32_16x16x32_bf16 v[86:89], v[188:191], v[220:223], v[86:89]
	v_mfma_f32_16x16x32_bf16 v[82:85], v[196:199], v[220:223], v[82:85]
	v_mfma_f32_16x16x32_bf16 v[70:73], v[188:191], v[228:231], v[70:73]
	v_mfma_f32_16x16x32_bf16 v[66:69], v[196:199], v[228:231], v[66:69]
	v_mfma_f32_16x16x32_bf16 v[118:121], v[192:195], v[208:211], v[118:121]
	v_mfma_f32_16x16x32_bf16 v[114:117], v[200:203], v[208:211], v[114:117]
	v_mfma_f32_16x16x32_bf16 v[102:105], v[192:195], v[216:219], v[102:105]
	v_mfma_f32_16x16x32_bf16 v[98:101], v[200:203], v[216:219], v[98:101]
	s_barrier
	v_mfma_f32_16x16x32_bf16 v[86:89], v[192:195], v[224:227], v[86:89]
	v_mfma_f32_16x16x32_bf16 v[82:85], v[200:203], v[224:227], v[82:85]
	v_mfma_f32_16x16x32_bf16 v[70:73], v[192:195], v[236:239], v[70:73]
	v_mfma_f32_16x16x32_bf16 v[66:69], v[200:203], v[236:239], v[66:69]
	s_setprio 0
	s_add_i32 s52, s69, s35
	v_lshl_add_u64 v[154:155], v[154:155], 0, s[16:17]
	s_mov_b32 m0, s52
	ds_read_b128 v[204:207], v173 offset:49152
	ds_read_b128 v[208:211], v173 offset:50176
	ds_read_b128 v[212:215], v173 offset:51200
	ds_read_b128 v[216:219], v173 offset:52224
	ds_read_b128 v[220:223], v173 offset:53248
	ds_read_b128 v[224:227], v173 offset:54272
	ds_read_b128 v[228:231], v173 offset:55296
	ds_read_b128 v[236:239], v173 offset:56320
	global_load_lds_dwordx4 v[154:155], off
	s_add_i32 m0, s52, 0x2000
	s_add_u32 s50, s50, 0x100080
	v_lshl_add_u64 v[154:155], v[158:159], 0, s[16:17]
	s_addc_u32 s51, s51, 0
	s_add_i32 s52, s70, s35
	global_load_lds_dwordx4 v[154:155], off
	v_lshl_add_u64 v[154:155], s[50:51], 0, v[132:133]
	s_mov_b32 m0, s52
	s_nop 0
	global_load_lds_dwordx4 v[154:155], off
	v_lshl_add_u64 v[154:155], s[50:51], 0, v[136:137]
	s_add_i32 m0, s52, 0x2000
	s_nop 0
	global_load_lds_dwordx4 v[154:155], off
	v_lshl_add_u64 v[154:155], v[162:163], 0, s[16:17]
	s_mov_b32 m0, s57
	s_nop 0
	global_load_lds_dwordx4 v[154:155], off
	v_lshl_add_u64 v[154:155], v[166:167], 0, s[16:17]
	s_mov_b32 m0, s58
	s_nop 0
	global_load_lds_dwordx4 v[154:155], off
	s_waitcnt vmcnt(8)
	s_waitcnt lgkmcnt(0)
	s_setprio 1
	s_barrier
	v_mfma_f32_16x16x32_bf16 v[62:65], v[148:151], v[204:207], v[62:65]
	v_mfma_f32_16x16x32_bf16 v[58:61], v[180:183], v[204:207], v[58:61]
	v_mfma_f32_16x16x32_bf16 v[46:49], v[148:151], v[212:215], v[46:49]
	v_mfma_f32_16x16x32_bf16 v[42:45], v[180:183], v[212:215], v[42:45]
	v_mfma_f32_16x16x32_bf16 v[30:33], v[148:151], v[220:223], v[30:33]
	v_mfma_f32_16x16x32_bf16 v[26:29], v[180:183], v[220:223], v[26:29]
	v_mfma_f32_16x16x32_bf16 v[14:17], v[148:151], v[228:231], v[14:17]
	v_mfma_f32_16x16x32_bf16 v[10:13], v[180:183], v[228:231], v[10:13]
	v_mfma_f32_16x16x32_bf16 v[62:65], v[174:177], v[208:211], v[62:65]
	v_mfma_f32_16x16x32_bf16 v[58:61], v[184:187], v[208:211], v[58:61]
	v_mfma_f32_16x16x32_bf16 v[46:49], v[174:177], v[216:219], v[46:49]
	v_mfma_f32_16x16x32_bf16 v[42:45], v[184:187], v[216:219], v[42:45]
	v_mfma_f32_16x16x32_bf16 v[30:33], v[174:177], v[224:227], v[30:33]
	v_mfma_f32_16x16x32_bf16 v[26:29], v[184:187], v[224:227], v[26:29]
	v_mfma_f32_16x16x32_bf16 v[14:17], v[174:177], v[236:239], v[14:17]
	v_mfma_f32_16x16x32_bf16 v[10:13], v[184:187], v[236:239], v[10:13]
	v_mfma_f32_16x16x32_bf16 v[54:57], v[188:191], v[204:207], v[54:57]
	v_mfma_f32_16x16x32_bf16 v[50:53], v[196:199], v[204:207], v[50:53]
	v_mfma_f32_16x16x32_bf16 v[38:41], v[188:191], v[212:215], v[38:41]
	v_mfma_f32_16x16x32_bf16 v[34:37], v[196:199], v[212:215], v[34:37]
	v_mfma_f32_16x16x32_bf16 v[22:25], v[188:191], v[220:223], v[22:25]
	v_mfma_f32_16x16x32_bf16 v[18:21], v[196:199], v[220:223], v[18:21]
	v_mfma_f32_16x16x32_bf16 v[6:9], v[188:191], v[228:231], v[6:9]
	v_mfma_f32_16x16x32_bf16 v[2:5], v[196:199], v[228:231], v[2:5]
	v_mfma_f32_16x16x32_bf16 v[54:57], v[192:195], v[208:211], v[54:57]
	v_mfma_f32_16x16x32_bf16 v[50:53], v[200:203], v[208:211], v[50:53]
	v_mfma_f32_16x16x32_bf16 v[38:41], v[192:195], v[216:219], v[38:41]
	v_mfma_f32_16x16x32_bf16 v[34:37], v[200:203], v[216:219], v[34:37]
	s_barrier
	v_mfma_f32_16x16x32_bf16 v[22:25], v[192:195], v[224:227], v[22:25]
	v_mfma_f32_16x16x32_bf16 v[18:21], v[200:203], v[224:227], v[18:21]
	v_mfma_f32_16x16x32_bf16 v[6:9], v[192:195], v[236:239], v[6:9]
	v_mfma_f32_16x16x32_bf16 v[2:5], v[200:203], v[236:239], v[2:5]
	s_setprio 0
	s_add_i32 s68, s68, 2
	s_add_u32 s4, s4, 0x100
	s_addc_u32 s5, s5, 0
	s_add_u32 s63, s63, 0x100
	s_addc_u32 s65, s65, 0
	s_cmp_gt_u32 s68, 61
	s_cbranch_scc0 .LBB0_446
	s_and_b64 vcc, exec, s[20:21]
	s_cbranch_vccz .LBB0_449
	s_barrier

.LBB0_668:
	ds_read_b128 v[154:157], v151
	ds_read_b128 v[158:161], v151 offset:1024
	ds_read_b128 v[162:165], v151 offset:2048
	ds_read_b128 v[166:169], v151 offset:3072
	ds_read_b128 v[170:173], v152
	ds_read_b128 v[174:177], v152 offset:1024
	ds_read_b128 v[178:181], v152 offset:2048
	ds_read_b128 v[182:185], v152 offset:3072
	s_add_u32 s36, s34, 0xfff00080
	s_addc_u32 s37, s35, -1
	s_cmp_eq_u32 s68, 60
	s_cselect_b32 s39, s25, s37
	s_cselect_b32 s38, s61, s36
	s_cselect_b32 s37, s23, s65
	s_cselect_b32 s36, s62, s63
	v_lshl_add_u64 v[148:149], s[34:35], 0, v[140:141]
	s_add_i32 m0, s31, 0xc000
	ds_read_b128 v[186:189], v153
	ds_read_b128 v[190:193], v153 offset:1024
	ds_read_b128 v[194:197], v153 offset:2048
	ds_read_b128 v[198:201], v153 offset:3072
	ds_read_b128 v[202:205], v153 offset:4096
	ds_read_b128 v[206:209], v153 offset:5120
	ds_read_b128 v[210:213], v153 offset:6144
	ds_read_b128 v[214:217], v153 offset:7168
	global_load_lds_dwordx4 v[148:149], off
	v_lshl_add_u64 v[148:149], s[34:35], 0, v[142:143]
	s_add_i32 m0, s31, 0xe000
	s_nop 0
	global_load_lds_dwordx4 v[148:149], off
	s_waitcnt vmcnt(8)
	s_waitcnt lgkmcnt(0)
	s_setprio 1
	s_barrier
	v_mfma_f32_16x16x32_bf16 v[126:129], v[154:157], v[186:189], v[126:129]
	v_mfma_f32_16x16x32_bf16 v[122:125], v[162:165], v[186:189], v[122:125]
	v_mfma_f32_16x16x32_bf16 v[114:117], v[154:157], v[194:197], v[114:117]
	v_mfma_f32_16x16x32_bf16 v[106:109], v[162:165], v[194:197], v[106:109]
	v_mfma_f32_16x16x32_bf16 v[98:101], v[154:157], v[202:205], v[98:101]
	v_mfma_f32_16x16x32_bf16 v[90:93], v[162:165], v[202:205], v[90:93]
	v_mfma_f32_16x16x32_bf16 v[82:85], v[154:157], v[210:213], v[82:85]
	v_mfma_f32_16x16x32_bf16 v[74:77], v[162:165], v[210:213], v[74:77]
	v_mfma_f32_16x16x32_bf16 v[126:129], v[158:161], v[190:193], v[126:129]
	v_mfma_f32_16x16x32_bf16 v[122:125], v[166:169], v[190:193], v[122:125]
	v_mfma_f32_16x16x32_bf16 v[114:117], v[158:161], v[198:201], v[114:117]
	v_mfma_f32_16x16x32_bf16 v[106:109], v[166:169], v[198:201], v[106:109]
	v_mfma_f32_16x16x32_bf16 v[98:101], v[158:161], v[206:209], v[98:101]
	v_mfma_f32_16x16x32_bf16 v[90:93], v[166:169], v[206:209], v[90:93]
	v_mfma_f32_16x16x32_bf16 v[82:85], v[158:161], v[214:217], v[82:85]
	v_mfma_f32_16x16x32_bf16 v[74:77], v[166:169], v[214:217], v[74:77]
	v_mfma_f32_16x16x32_bf16 v[118:121], v[170:173], v[186:189], v[118:121]
	v_mfma_f32_16x16x32_bf16 v[110:113], v[178:181], v[186:189], v[110:113]
	v_mfma_f32_16x16x32_bf16 v[102:105], v[170:173], v[194:197], v[102:105]
	v_mfma_f32_16x16x32_bf16 v[94:97], v[178:181], v[194:197], v[94:97]
	v_mfma_f32_16x16x32_bf16 v[86:89], v[170:173], v[202:205], v[86:89]
	v_mfma_f32_16x16x32_bf16 v[78:81], v[178:181], v[202:205], v[78:81]
	v_mfma_f32_16x16x32_bf16 v[70:73], v[170:173], v[210:213], v[70:73]
	v_mfma_f32_16x16x32_bf16 v[66:69], v[178:181], v[210:213], v[66:69]
	v_mfma_f32_16x16x32_bf16 v[118:121], v[174:177], v[190:193], v[118:121]
	v_mfma_f32_16x16x32_bf16 v[110:113], v[182:185], v[190:193], v[110:113]
	v_mfma_f32_16x16x32_bf16 v[102:105], v[174:177], v[198:201], v[102:105]
	v_mfma_f32_16x16x32_bf16 v[94:97], v[182:185], v[198:201], v[94:97]
	s_barrier
	v_mfma_f32_16x16x32_bf16 v[86:89], v[174:177], v[206:209], v[86:89]
	v_mfma_f32_16x16x32_bf16 v[78:81], v[182:185], v[206:209], v[78:81]
	v_mfma_f32_16x16x32_bf16 v[70:73], v[174:177], v[214:217], v[70:73]
	v_mfma_f32_16x16x32_bf16 v[66:69], v[182:185], v[214:217], v[66:69]
	s_setprio 0
	s_add_i32 s69, s54, s47
	v_lshl_add_u64 v[148:149], s[36:37], 0, v[136:137]
	s_mov_b32 m0, s69
	ds_read_b128 v[186:189], v153 offset:16384
	ds_read_b128 v[190:193], v153 offset:17408
	ds_read_b128 v[194:197], v153 offset:18432
	ds_read_b128 v[198:201], v153 offset:19456
	ds_read_b128 v[202:205], v153 offset:20480
	ds_read_b128 v[206:209], v153 offset:21504
	ds_read_b128 v[210:213], v153 offset:22528
	ds_read_b128 v[214:217], v153 offset:23552
	global_load_lds_dwordx4 v[148:149], off
	s_add_i32 m0, s69, 0x2000
	s_add_u32 s70, s36, 0x100000
	v_lshl_add_u64 v[218:219], s[36:37], 0, v[132:133]
	s_addc_u32 s71, s37, 0
	s_add_i32 s69, s55, s47
	global_load_lds_dwordx4 v[218:219], off
	v_lshl_add_u64 v[220:221], s[70:71], 0, v[136:137]
	s_mov_b32 m0, s69
	v_lshl_add_u64 v[222:223], s[38:39], 0, v[134:135]
	global_load_lds_dwordx4 v[220:221], off
	v_lshl_add_u64 v[220:221], s[70:71], 0, v[132:133]
	s_add_i32 m0, s69, 0x2000
	s_nop 0
	global_load_lds_dwordx4 v[220:221], off
	v_lshl_add_u64 v[220:221], s[38:39], 0, v[138:139]
	s_mov_b32 m0, s31
	s_nop 0
	global_load_lds_dwordx4 v[220:221], off
	s_mov_b32 m0, s48
	s_nop 0
	global_load_lds_dwordx4 v[222:223], off
	s_waitcnt vmcnt(8)
	s_waitcnt lgkmcnt(0)
	s_setprio 1
	s_barrier
	v_mfma_f32_16x16x32_bf16 v[62:65], v[154:157], v[186:189], v[62:65]
	v_mfma_f32_16x16x32_bf16 v[58:61], v[162:165], v[186:189], v[58:61]
	v_mfma_f32_16x16x32_bf16 v[50:53], v[154:157], v[194:197], v[50:53]
	v_mfma_f32_16x16x32_bf16 v[42:45], v[162:165], v[194:197], v[42:45]
	v_mfma_f32_16x16x32_bf16 v[34:37], v[154:157], v[202:205], v[34:37]
	v_mfma_f32_16x16x32_bf16 v[26:29], v[162:165], v[202:205], v[26:29]
	v_mfma_f32_16x16x32_bf16 v[18:21], v[154:157], v[210:213], v[18:21]
	v_mfma_f32_16x16x32_bf16 v[10:13], v[162:165], v[210:213], v[10:13]
	v_mfma_f32_16x16x32_bf16 v[62:65], v[158:161], v[190:193], v[62:65]
	v_mfma_f32_16x16x32_bf16 v[58:61], v[166:169], v[190:193], v[58:61]
	v_mfma_f32_16x16x32_bf16 v[50:53], v[158:161], v[198:201], v[50:53]
	v_mfma_f32_16x16x32_bf16 v[42:45], v[166:169], v[198:201], v[42:45]
	v_mfma_f32_16x16x32_bf16 v[34:37], v[158:161], v[206:209], v[34:37]
	v_mfma_f32_16x16x32_bf16 v[26:29], v[166:169], v[206:209], v[26:29]
	v_mfma_f32_16x16x32_bf16 v[18:21], v[158:161], v[214:217], v[18:21]
	v_mfma_f32_16x16x32_bf16 v[10:13], v[166:169], v[214:217], v[10:13]
	v_mfma_f32_16x16x32_bf16 v[54:57], v[170:173], v[186:189], v[54:57]
	v_mfma_f32_16x16x32_bf16 v[46:49], v[178:181], v[186:189], v[46:49]
	v_mfma_f32_16x16x32_bf16 v[38:41], v[170:173], v[194:197], v[38:41]
	v_mfma_f32_16x16x32_bf16 v[30:33], v[178:181], v[194:197], v[30:33]
	v_mfma_f32_16x16x32_bf16 v[22:25], v[170:173], v[202:205], v[22:25]
	v_mfma_f32_16x16x32_bf16 v[14:17], v[178:181], v[202:205], v[14:17]
	v_mfma_f32_16x16x32_bf16 v[6:9], v[170:173], v[210:213], v[6:9]
	v_mfma_f32_16x16x32_bf16 v[2:5], v[178:181], v[210:213], v[2:5]
	v_mfma_f32_16x16x32_bf16 v[54:57], v[174:177], v[190:193], v[54:57]
	v_mfma_f32_16x16x32_bf16 v[46:49], v[182:185], v[190:193], v[46:49]
	v_mfma_f32_16x16x32_bf16 v[38:41], v[174:177], v[198:201], v[38:41]
	v_mfma_f32_16x16x32_bf16 v[30:33], v[182:185], v[198:201], v[30:33]
	s_barrier
	v_mfma_f32_16x16x32_bf16 v[22:25], v[174:177], v[206:209], v[22:25]
	v_mfma_f32_16x16x32_bf16 v[14:17], v[182:185], v[206:209], v[14:17]
	v_mfma_f32_16x16x32_bf16 v[6:9], v[174:177], v[214:217], v[6:9]
	v_mfma_f32_16x16x32_bf16 v[2:5], v[182:185], v[214:217], v[2:5]
	s_setprio 0
	s_add_i32 s69, 0, 0x18000
	s_add_i32 s70, 0, 0x1c000
	v_add_u32_e32 v166, s69, v131
	v_add_u32_e32 v182, s70, v131
	ds_read_b128 v[154:157], v166
	ds_read_b128 v[158:161], v166 offset:1024
	ds_read_b128 v[162:165], v166 offset:2048
	ds_read_b128 v[166:169], v166 offset:3072
	ds_read_b128 v[170:173], v182
	ds_read_b128 v[174:177], v182 offset:1024
	ds_read_b128 v[178:181], v182 offset:2048
	ds_read_b128 v[182:185], v182 offset:3072
	s_add_u32 s38, s38, 0x100000
	s_addc_u32 s39, s39, 0
	s_mov_b32 m0, s49
	v_lshl_add_u64 v[224:225], s[38:39], 0, v[138:139]
	ds_read_b128 v[186:189], v153 offset:32768
	ds_read_b128 v[190:193], v153 offset:33792
	ds_read_b128 v[194:197], v153 offset:34816
	ds_read_b128 v[198:201], v153 offset:35840
	ds_read_b128 v[202:205], v153 offset:36864
	ds_read_b128 v[206:209], v153 offset:37888
	ds_read_b128 v[210:213], v153 offset:38912
	ds_read_b128 v[214:217], v153 offset:39936
	global_load_lds_dwordx4 v[224:225], off
	v_lshl_add_u64 v[224:225], s[38:39], 0, v[134:135]
	s_mov_b32 m0, s50
	s_nop 0
	global_load_lds_dwordx4 v[224:225], off
	s_waitcnt vmcnt(8)
	s_waitcnt lgkmcnt(0)
	s_setprio 1
	s_barrier
	v_mfma_f32_16x16x32_bf16 v[126:129], v[154:157], v[186:189], v[126:129]
	v_mfma_f32_16x16x32_bf16 v[122:125], v[162:165], v[186:189], v[122:125]
	v_mfma_f32_16x16x32_bf16 v[114:117], v[154:157], v[194:197], v[114:117]
	v_mfma_f32_16x16x32_bf16 v[106:109], v[162:165], v[194:197], v[106:109]
	v_mfma_f32_16x16x32_bf16 v[98:101], v[154:157], v[202:205], v[98:101]
	v_mfma_f32_16x16x32_bf16 v[90:93], v[162:165], v[202:205], v[90:93]
	v_mfma_f32_16x16x32_bf16 v[82:85], v[154:157], v[210:213], v[82:85]
	v_mfma_f32_16x16x32_bf16 v[74:77], v[162:165], v[210:213], v[74:77]
	v_mfma_f32_16x16x32_bf16 v[126:129], v[158:161], v[190:193], v[126:129]
	v_mfma_f32_16x16x32_bf16 v[122:125], v[166:169], v[190:193], v[122:125]
	v_mfma_f32_16x16x32_bf16 v[114:117], v[158:161], v[198:201], v[114:117]
	v_mfma_f32_16x16x32_bf16 v[106:109], v[166:169], v[198:201], v[106:109]
	v_mfma_f32_16x16x32_bf16 v[98:101], v[158:161], v[206:209], v[98:101]
	v_mfma_f32_16x16x32_bf16 v[90:93], v[166:169], v[206:209], v[90:93]
	v_mfma_f32_16x16x32_bf16 v[82:85], v[158:161], v[214:217], v[82:85]
	v_mfma_f32_16x16x32_bf16 v[74:77], v[166:169], v[214:217], v[74:77]
	v_mfma_f32_16x16x32_bf16 v[118:121], v[170:173], v[186:189], v[118:121]
	v_mfma_f32_16x16x32_bf16 v[110:113], v[178:181], v[186:189], v[110:113]
	v_mfma_f32_16x16x32_bf16 v[102:105], v[170:173], v[194:197], v[102:105]
	v_mfma_f32_16x16x32_bf16 v[94:97], v[178:181], v[194:197], v[94:97]
	v_mfma_f32_16x16x32_bf16 v[86:89], v[170:173], v[202:205], v[86:89]
	v_mfma_f32_16x16x32_bf16 v[78:81], v[178:181], v[202:205], v[78:81]
	v_mfma_f32_16x16x32_bf16 v[70:73], v[170:173], v[210:213], v[70:73]
	v_mfma_f32_16x16x32_bf16 v[66:69], v[178:181], v[210:213], v[66:69]
	v_mfma_f32_16x16x32_bf16 v[118:121], v[174:177], v[190:193], v[118:121]
	v_mfma_f32_16x16x32_bf16 v[110:113], v[182:185], v[190:193], v[110:113]
	v_mfma_f32_16x16x32_bf16 v[102:105], v[174:177], v[198:201], v[102:105]
	v_mfma_f32_16x16x32_bf16 v[94:97], v[182:185], v[198:201], v[94:97]
	s_barrier
	v_mfma_f32_16x16x32_bf16 v[86:89], v[174:177], v[206:209], v[86:89]
	v_mfma_f32_16x16x32_bf16 v[78:81], v[182:185], v[206:209], v[78:81]
	v_mfma_f32_16x16x32_bf16 v[70:73], v[174:177], v[214:217], v[70:73]
	v_mfma_f32_16x16x32_bf16 v[66:69], v[182:185], v[214:217], v[66:69]
	s_setprio 0
	s_add_i32 s38, s69, s47
	v_lshl_add_u64 v[148:149], v[148:149], 0, s[8:9]
	s_mov_b32 m0, s38
	ds_read_b128 v[186:189], v153 offset:49152
	ds_read_b128 v[190:193], v153 offset:50176
	ds_read_b128 v[194:197], v153 offset:51200
	ds_read_b128 v[198:201], v153 offset:52224
	ds_read_b128 v[202:205], v153 offset:53248
	ds_read_b128 v[206:209], v153 offset:54272
	ds_read_b128 v[210:213], v153 offset:55296
	ds_read_b128 v[214:217], v153 offset:56320
	global_load_lds_dwordx4 v[148:149], off
	s_add_i32 m0, s38, 0x2000
	s_add_u32 s36, s36, 0x100080
	v_lshl_add_u64 v[148:149], v[218:219], 0, s[8:9]
	s_addc_u32 s37, s37, 0
	s_add_i32 s38, s70, s47
	global_load_lds_dwordx4 v[148:149], off
	v_lshl_add_u64 v[148:149], s[36:37], 0, v[136:137]
	s_mov_b32 m0, s38
	s_nop 0
	global_load_lds_dwordx4 v[148:149], off
	v_lshl_add_u64 v[148:149], s[36:37], 0, v[132:133]
	s_add_i32 m0, s38, 0x2000
	s_nop 0
	global_load_lds_dwordx4 v[148:149], off
	v_lshl_add_u64 v[148:149], v[220:221], 0, s[8:9]
	s_mov_b32 m0, s52
	s_nop 0
	global_load_lds_dwordx4 v[148:149], off
	v_lshl_add_u64 v[148:149], v[222:223], 0, s[8:9]
	s_mov_b32 m0, s53
	s_nop 0
	global_load_lds_dwordx4 v[148:149], off
	s_waitcnt vmcnt(8)
	s_waitcnt lgkmcnt(0)
	s_setprio 1
	s_barrier
	v_mfma_f32_16x16x32_bf16 v[62:65], v[154:157], v[186:189], v[62:65]
	v_mfma_f32_16x16x32_bf16 v[58:61], v[162:165], v[186:189], v[58:61]
	v_mfma_f32_16x16x32_bf16 v[50:53], v[154:157], v[194:197], v[50:53]
	v_mfma_f32_16x16x32_bf16 v[42:45], v[162:165], v[194:197], v[42:45]
	v_mfma_f32_16x16x32_bf16 v[34:37], v[154:157], v[202:205], v[34:37]
	v_mfma_f32_16x16x32_bf16 v[26:29], v[162:165], v[202:205], v[26:29]
	v_mfma_f32_16x16x32_bf16 v[18:21], v[154:157], v[210:213], v[18:21]
	v_mfma_f32_16x16x32_bf16 v[10:13], v[162:165], v[210:213], v[10:13]
	v_mfma_f32_16x16x32_bf16 v[62:65], v[158:161], v[190:193], v[62:65]
	v_mfma_f32_16x16x32_bf16 v[58:61], v[166:169], v[190:193], v[58:61]
	v_mfma_f32_16x16x32_bf16 v[50:53], v[158:161], v[198:201], v[50:53]
	v_mfma_f32_16x16x32_bf16 v[42:45], v[166:169], v[198:201], v[42:45]
	v_mfma_f32_16x16x32_bf16 v[34:37], v[158:161], v[206:209], v[34:37]
	v_mfma_f32_16x16x32_bf16 v[26:29], v[166:169], v[206:209], v[26:29]
	v_mfma_f32_16x16x32_bf16 v[18:21], v[158:161], v[214:217], v[18:21]
	v_mfma_f32_16x16x32_bf16 v[10:13], v[166:169], v[214:217], v[10:13]
	v_mfma_f32_16x16x32_bf16 v[54:57], v[170:173], v[186:189], v[54:57]
	v_mfma_f32_16x16x32_bf16 v[46:49], v[178:181], v[186:189], v[46:49]
	v_mfma_f32_16x16x32_bf16 v[38:41], v[170:173], v[194:197], v[38:41]
	v_mfma_f32_16x16x32_bf16 v[30:33], v[178:181], v[194:197], v[30:33]
	v_mfma_f32_16x16x32_bf16 v[22:25], v[170:173], v[202:205], v[22:25]
	v_mfma_f32_16x16x32_bf16 v[14:17], v[178:181], v[202:205], v[14:17]
	v_mfma_f32_16x16x32_bf16 v[6:9], v[170:173], v[210:213], v[6:9]
	v_mfma_f32_16x16x32_bf16 v[2:5], v[178:181], v[210:213], v[2:5]
	v_mfma_f32_16x16x32_bf16 v[54:57], v[174:177], v[190:193], v[54:57]
	v_mfma_f32_16x16x32_bf16 v[46:49], v[182:185], v[190:193], v[46:49]
	v_mfma_f32_16x16x32_bf16 v[38:41], v[174:177], v[198:201], v[38:41]
	v_mfma_f32_16x16x32_bf16 v[30:33], v[182:185], v[198:201], v[30:33]
	s_barrier
	v_mfma_f32_16x16x32_bf16 v[22:25], v[174:177], v[206:209], v[22:25]
	v_mfma_f32_16x16x32_bf16 v[14:17], v[182:185], v[206:209], v[14:17]
	v_mfma_f32_16x16x32_bf16 v[6:9], v[174:177], v[214:217], v[6:9]
	v_mfma_f32_16x16x32_bf16 v[2:5], v[182:185], v[214:217], v[2:5]
	s_setprio 0
	s_add_i32 s68, s68, 2
	s_add_u32 s34, s34, 0x100
	s_addc_u32 s35, s35, 0
	s_add_u32 s63, s63, 0x100
	s_addc_u32 s65, s65, 0
	s_cmp_gt_u32 s68, 61
	s_cbranch_scc0 .LBB0_668
	s_and_b64 vcc, exec, s[12:13]
	s_cbranch_vccz .LBB0_671
	s_barrier

.LBB0_845:
	ds_read_b128 v[130:133], v238
	ds_read_b128 v[134:137], v238 offset:1024
	ds_read_b128 v[138:141], v238 offset:2048
	ds_read_b128 v[142:145], v238 offset:3072
	ds_read_b128 v[146:149], v239
	ds_read_b128 v[150:153], v239 offset:1024
	ds_read_b128 v[154:157], v239 offset:2048
	ds_read_b128 v[158:161], v239 offset:3072
	s_add_u32 s56, s2, 0x100
	s_addc_u32 s57, s3, 0
	s_cmp_eq_u32 s92, 28
	s_cselect_b32 s61, s49, s57
	s_cselect_b32 s60, s88, s56
	s_cselect_b32 s59, s47, s91
	s_cselect_b32 s58, s89, s90
	v_lshl_add_u64 v[194:195], s[2:3], 0, v[210:211]
	s_add_i32 m0, s55, 0xc000
	ds_read_b128 v[162:165], v240
	ds_read_b128 v[166:169], v240 offset:1024
	ds_read_b128 v[170:173], v240 offset:2048
	ds_read_b128 v[174:177], v240 offset:3072
	ds_read_b128 v[178:181], v240 offset:4096
	ds_read_b128 v[182:185], v240 offset:5120
	ds_read_b128 v[186:189], v240 offset:6144
	ds_read_b128 v[190:193], v240 offset:7168
	global_load_lds_dwordx4 v[194:195], off
	v_lshl_add_u64 v[194:195], s[2:3], 0, v[212:213]
	s_add_i32 m0, s55, 0xe000
	s_nop 0
	global_load_lds_dwordx4 v[194:195], off
	s_waitcnt vmcnt(8)
	s_waitcnt lgkmcnt(0)
	s_setprio 1
	s_barrier
	v_mfma_i32_16x16x64_i8 v[126:129], v[130:133], v[162:165], v[126:129]
	v_mfma_i32_16x16x64_i8 v[122:125], v[138:141], v[162:165], v[122:125]
	v_mfma_i32_16x16x64_i8 v[118:121], v[130:133], v[170:173], v[118:121]
	v_mfma_i32_16x16x64_i8 v[110:113], v[138:141], v[170:173], v[110:113]
	v_mfma_i32_16x16x64_i8 v[78:81], v[130:133], v[178:181], v[78:81]
	v_mfma_i32_16x16x64_i8 v[30:33], v[138:141], v[178:181], v[30:33]
	v_mfma_i32_16x16x64_i8 v[74:77], v[130:133], v[186:189], v[74:77]
	v_mfma_i32_16x16x64_i8 v[26:29], v[138:141], v[186:189], v[26:29]
	v_mfma_i32_16x16x64_i8 v[126:129], v[134:137], v[166:169], v[126:129]
	v_mfma_i32_16x16x64_i8 v[122:125], v[142:145], v[166:169], v[122:125]
	v_mfma_i32_16x16x64_i8 v[118:121], v[134:137], v[174:177], v[118:121]
	v_mfma_i32_16x16x64_i8 v[110:113], v[142:145], v[174:177], v[110:113]
	v_mfma_i32_16x16x64_i8 v[78:81], v[134:137], v[182:185], v[78:81]
	v_mfma_i32_16x16x64_i8 v[30:33], v[142:145], v[182:185], v[30:33]
	v_mfma_i32_16x16x64_i8 v[74:77], v[134:137], v[190:193], v[74:77]
	v_mfma_i32_16x16x64_i8 v[26:29], v[142:145], v[190:193], v[26:29]
	v_mfma_i32_16x16x64_i8 v[102:105], v[146:149], v[162:165], v[102:105]
	v_mfma_i32_16x16x64_i8 v[98:101], v[154:157], v[162:165], v[98:101]
	v_mfma_i32_16x16x64_i8 v[94:97], v[146:149], v[170:173], v[94:97]
	v_mfma_i32_16x16x64_i8 v[90:93], v[154:157], v[170:173], v[90:93]
	v_mfma_i32_16x16x64_i8 v[70:73], v[146:149], v[178:181], v[70:73]
	v_mfma_i32_16x16x64_i8 v[22:25], v[154:157], v[178:181], v[22:25]
	v_mfma_i32_16x16x64_i8 v[66:69], v[146:149], v[186:189], v[66:69]
	v_mfma_i32_16x16x64_i8 v[18:21], v[154:157], v[186:189], v[18:21]
	v_mfma_i32_16x16x64_i8 v[102:105], v[150:153], v[166:169], v[102:105]
	v_mfma_i32_16x16x64_i8 v[98:101], v[158:161], v[166:169], v[98:101]
	v_mfma_i32_16x16x64_i8 v[94:97], v[150:153], v[174:177], v[94:97]
	v_mfma_i32_16x16x64_i8 v[90:93], v[158:161], v[174:177], v[90:93]
	s_barrier
	v_mfma_i32_16x16x64_i8 v[70:73], v[150:153], v[182:185], v[70:73]
	v_mfma_i32_16x16x64_i8 v[22:25], v[158:161], v[182:185], v[22:25]
	v_mfma_i32_16x16x64_i8 v[66:69], v[150:153], v[190:193], v[66:69]
	v_mfma_i32_16x16x64_i8 v[18:21], v[158:161], v[190:193], v[18:21]
	s_setprio 0
	s_add_i32 s2, s84, s65
	v_lshl_add_u64 v[194:195], s[58:59], 0, v[206:207]
	s_mov_b32 m0, s2
	ds_read_b128 v[162:165], v240 offset:16384
	ds_read_b128 v[166:169], v240 offset:17408
	ds_read_b128 v[170:173], v240 offset:18432
	ds_read_b128 v[174:177], v240 offset:19456
	ds_read_b128 v[178:181], v240 offset:20480
	ds_read_b128 v[182:185], v240 offset:21504
	ds_read_b128 v[186:189], v240 offset:22528
	ds_read_b128 v[190:193], v240 offset:23552
	global_load_lds_dwordx4 v[194:195], off
	s_add_i32 m0, s2, 0x2000
	s_add_u32 s2, s58, 0x80000
	v_lshl_add_u64 v[196:197], s[58:59], 0, v[202:203]
	s_addc_u32 s3, s59, 0
	s_add_i32 s93, s85, s65
	global_load_lds_dwordx4 v[196:197], off
	v_lshl_add_u64 v[198:199], s[2:3], 0, v[206:207]
	s_mov_b32 m0, s93
	v_lshl_add_u64 v[200:201], s[60:61], 0, v[204:205]
	global_load_lds_dwordx4 v[198:199], off
	v_lshl_add_u64 v[198:199], s[2:3], 0, v[202:203]
	s_add_i32 m0, s93, 0x2000
	s_nop 0
	global_load_lds_dwordx4 v[198:199], off
	v_lshl_add_u64 v[198:199], s[60:61], 0, v[208:209]
	s_mov_b32 m0, s55
	s_nop 0
	global_load_lds_dwordx4 v[198:199], off
	s_mov_b32 m0, s69
	s_nop 0
	global_load_lds_dwordx4 v[200:201], off
	s_waitcnt vmcnt(8)
	s_waitcnt lgkmcnt(0)
	s_setprio 1
	s_barrier
	v_mfma_i32_16x16x64_i8 v[62:65], v[130:133], v[162:165], v[62:65]
	v_mfma_i32_16x16x64_i8 v[14:17], v[138:141], v[162:165], v[14:17]
	v_mfma_i32_16x16x64_i8 v[58:61], v[130:133], v[170:173], v[58:61]
	v_mfma_i32_16x16x64_i8 v[10:13], v[138:141], v[170:173], v[10:13]
	v_mfma_i32_16x16x64_i8 v[114:117], v[130:133], v[178:181], v[114:117]
	v_mfma_i32_16x16x64_i8 v[106:109], v[138:141], v[178:181], v[106:109]
	v_mfma_i32_16x16x64_i8 v[86:89], v[130:133], v[186:189], v[86:89]
	v_mfma_i32_16x16x64_i8 v[82:85], v[138:141], v[186:189], v[82:85]
	v_mfma_i32_16x16x64_i8 v[62:65], v[134:137], v[166:169], v[62:65]
	v_mfma_i32_16x16x64_i8 v[14:17], v[142:145], v[166:169], v[14:17]
	v_mfma_i32_16x16x64_i8 v[58:61], v[134:137], v[174:177], v[58:61]
	v_mfma_i32_16x16x64_i8 v[10:13], v[142:145], v[174:177], v[10:13]
	v_mfma_i32_16x16x64_i8 v[114:117], v[134:137], v[182:185], v[114:117]
	v_mfma_i32_16x16x64_i8 v[106:109], v[142:145], v[182:185], v[106:109]
	v_mfma_i32_16x16x64_i8 v[86:89], v[134:137], v[190:193], v[86:89]
	v_mfma_i32_16x16x64_i8 v[82:85], v[142:145], v[190:193], v[82:85]
	v_mfma_i32_16x16x64_i8 v[50:53], v[146:149], v[162:165], v[50:53]
	v_mfma_i32_16x16x64_i8 v[6:9], v[154:157], v[162:165], v[6:9]
	v_mfma_i32_16x16x64_i8 v[42:45], v[146:149], v[170:173], v[42:45]
	v_mfma_i32_16x16x64_i8 v[2:5], v[154:157], v[170:173], v[2:5]
	v_mfma_i32_16x16x64_i8 v[54:57], v[146:149], v[178:181], v[54:57]
	v_mfma_i32_16x16x64_i8 v[46:49], v[154:157], v[178:181], v[46:49]
	v_mfma_i32_16x16x64_i8 v[38:41], v[146:149], v[186:189], v[38:41]
	v_mfma_i32_16x16x64_i8 v[34:37], v[154:157], v[186:189], v[34:37]
	v_mfma_i32_16x16x64_i8 v[50:53], v[150:153], v[166:169], v[50:53]
	v_mfma_i32_16x16x64_i8 v[6:9], v[158:161], v[166:169], v[6:9]
	v_mfma_i32_16x16x64_i8 v[42:45], v[150:153], v[174:177], v[42:45]
	v_mfma_i32_16x16x64_i8 v[2:5], v[158:161], v[174:177], v[2:5]
	s_barrier
	v_mfma_i32_16x16x64_i8 v[54:57], v[150:153], v[182:185], v[54:57]
	v_mfma_i32_16x16x64_i8 v[46:49], v[158:161], v[182:185], v[46:49]
	v_mfma_i32_16x16x64_i8 v[38:41], v[150:153], v[190:193], v[38:41]
	v_mfma_i32_16x16x64_i8 v[34:37], v[158:161], v[190:193], v[34:37]
	s_setprio 0
	s_add_i32 s93, 0, 0x18000
	s_add_i32 s94, 0, 0x1c000
	v_add_u32_e32 v142, s93, v237
	v_add_u32_e32 v158, s94, v237
	ds_read_b128 v[130:133], v142
	ds_read_b128 v[134:137], v142 offset:1024
	ds_read_b128 v[138:141], v142 offset:2048
	ds_read_b128 v[142:145], v142 offset:3072
	ds_read_b128 v[146:149], v158
	ds_read_b128 v[150:153], v158 offset:1024
	ds_read_b128 v[154:157], v158 offset:2048
	ds_read_b128 v[158:161], v158 offset:3072
	s_add_u32 s2, s60, 0x4000
	s_addc_u32 s3, s61, 0
	s_mov_b32 m0, s70
	v_lshl_add_u64 v[220:221], s[2:3], 0, v[208:209]
	ds_read_b128 v[162:165], v240 offset:32768
	ds_read_b128 v[166:169], v240 offset:33792
	ds_read_b128 v[170:173], v240 offset:34816
	ds_read_b128 v[174:177], v240 offset:35840
	ds_read_b128 v[178:181], v240 offset:36864
	ds_read_b128 v[182:185], v240 offset:37888
	ds_read_b128 v[186:189], v240 offset:38912
	ds_read_b128 v[190:193], v240 offset:39936
	global_load_lds_dwordx4 v[220:221], off
	v_lshl_add_u64 v[220:221], s[2:3], 0, v[204:205]
	s_mov_b32 m0, s71
	s_nop 0
	global_load_lds_dwordx4 v[220:221], off
	s_waitcnt vmcnt(8)
	s_waitcnt lgkmcnt(0)
	s_setprio 1
	s_barrier
	v_mfma_i32_16x16x64_i8 v[126:129], v[130:133], v[162:165], v[126:129]
	v_mfma_i32_16x16x64_i8 v[122:125], v[138:141], v[162:165], v[122:125]
	v_mfma_i32_16x16x64_i8 v[118:121], v[130:133], v[170:173], v[118:121]
	v_mfma_i32_16x16x64_i8 v[110:113], v[138:141], v[170:173], v[110:113]
	v_mfma_i32_16x16x64_i8 v[78:81], v[130:133], v[178:181], v[78:81]
	v_mfma_i32_16x16x64_i8 v[30:33], v[138:141], v[178:181], v[30:33]
	v_mfma_i32_16x16x64_i8 v[74:77], v[130:133], v[186:189], v[74:77]
	v_mfma_i32_16x16x64_i8 v[26:29], v[138:141], v[186:189], v[26:29]
	v_mfma_i32_16x16x64_i8 v[126:129], v[134:137], v[166:169], v[126:129]
	v_mfma_i32_16x16x64_i8 v[122:125], v[142:145], v[166:169], v[122:125]
	v_mfma_i32_16x16x64_i8 v[118:121], v[134:137], v[174:177], v[118:121]
	v_mfma_i32_16x16x64_i8 v[110:113], v[142:145], v[174:177], v[110:113]
	v_mfma_i32_16x16x64_i8 v[78:81], v[134:137], v[182:185], v[78:81]
	v_mfma_i32_16x16x64_i8 v[30:33], v[142:145], v[182:185], v[30:33]
	v_mfma_i32_16x16x64_i8 v[74:77], v[134:137], v[190:193], v[74:77]
	v_mfma_i32_16x16x64_i8 v[26:29], v[142:145], v[190:193], v[26:29]
	v_mfma_i32_16x16x64_i8 v[102:105], v[146:149], v[162:165], v[102:105]
	v_mfma_i32_16x16x64_i8 v[98:101], v[154:157], v[162:165], v[98:101]
	v_mfma_i32_16x16x64_i8 v[94:97], v[146:149], v[170:173], v[94:97]
	v_mfma_i32_16x16x64_i8 v[90:93], v[154:157], v[170:173], v[90:93]
	v_mfma_i32_16x16x64_i8 v[70:73], v[146:149], v[178:181], v[70:73]
	v_mfma_i32_16x16x64_i8 v[22:25], v[154:157], v[178:181], v[22:25]
	v_mfma_i32_16x16x64_i8 v[66:69], v[146:149], v[186:189], v[66:69]
	v_mfma_i32_16x16x64_i8 v[18:21], v[154:157], v[186:189], v[18:21]
	v_mfma_i32_16x16x64_i8 v[102:105], v[150:153], v[166:169], v[102:105]
	v_mfma_i32_16x16x64_i8 v[98:101], v[158:161], v[166:169], v[98:101]
	v_mfma_i32_16x16x64_i8 v[94:97], v[150:153], v[174:177], v[94:97]
	v_mfma_i32_16x16x64_i8 v[90:93], v[158:161], v[174:177], v[90:93]
	s_barrier
	v_mfma_i32_16x16x64_i8 v[70:73], v[150:153], v[182:185], v[70:73]
	v_mfma_i32_16x16x64_i8 v[22:25], v[158:161], v[182:185], v[22:25]
	v_mfma_i32_16x16x64_i8 v[66:69], v[150:153], v[190:193], v[66:69]
	v_mfma_i32_16x16x64_i8 v[18:21], v[158:161], v[190:193], v[18:21]
	s_setprio 0
	s_add_i32 s2, s93, s65
	v_lshl_add_u64 v[194:195], v[194:195], 0, s[36:37]
	s_mov_b32 m0, s2
	ds_read_b128 v[162:165], v240 offset:49152
	ds_read_b128 v[166:169], v240 offset:50176
	ds_read_b128 v[170:173], v240 offset:51200
	ds_read_b128 v[174:177], v240 offset:52224
	ds_read_b128 v[178:181], v240 offset:53248
	ds_read_b128 v[182:185], v240 offset:54272
	ds_read_b128 v[186:189], v240 offset:55296
	ds_read_b128 v[190:193], v240 offset:56320
	global_load_lds_dwordx4 v[194:195], off
	s_add_i32 m0, s2, 0x2000
	s_add_u32 s2, s58, 0x80080
	v_lshl_add_u64 v[194:195], v[196:197], 0, s[36:37]
	s_addc_u32 s3, s59, 0
	s_add_i32 s58, s94, s65
	global_load_lds_dwordx4 v[194:195], off
	v_lshl_add_u64 v[194:195], s[2:3], 0, v[206:207]
	s_mov_b32 m0, s58
	s_nop 0
	global_load_lds_dwordx4 v[194:195], off
	v_lshl_add_u64 v[194:195], s[2:3], 0, v[202:203]
	s_add_i32 m0, s58, 0x2000
	s_nop 0
	global_load_lds_dwordx4 v[194:195], off
	v_lshl_add_u64 v[194:195], v[198:199], 0, s[36:37]
	s_mov_b32 m0, s78
	s_nop 0
	global_load_lds_dwordx4 v[194:195], off
	v_lshl_add_u64 v[194:195], v[200:201], 0, s[36:37]
	s_mov_b32 m0, s79
	s_nop 0
	global_load_lds_dwordx4 v[194:195], off
	s_waitcnt vmcnt(8)
	s_waitcnt lgkmcnt(0)
	s_setprio 1
	s_barrier
	v_mfma_i32_16x16x64_i8 v[62:65], v[130:133], v[162:165], v[62:65]
	v_mfma_i32_16x16x64_i8 v[14:17], v[138:141], v[162:165], v[14:17]
	v_mfma_i32_16x16x64_i8 v[58:61], v[130:133], v[170:173], v[58:61]
	v_mfma_i32_16x16x64_i8 v[10:13], v[138:141], v[170:173], v[10:13]
	v_mfma_i32_16x16x64_i8 v[114:117], v[130:133], v[178:181], v[114:117]
	v_mfma_i32_16x16x64_i8 v[106:109], v[138:141], v[178:181], v[106:109]
	v_mfma_i32_16x16x64_i8 v[86:89], v[130:133], v[186:189], v[86:89]
	v_mfma_i32_16x16x64_i8 v[82:85], v[138:141], v[186:189], v[82:85]
	v_mfma_i32_16x16x64_i8 v[62:65], v[134:137], v[166:169], v[62:65]
	v_mfma_i32_16x16x64_i8 v[14:17], v[142:145], v[166:169], v[14:17]
	v_mfma_i32_16x16x64_i8 v[58:61], v[134:137], v[174:177], v[58:61]
	v_mfma_i32_16x16x64_i8 v[10:13], v[142:145], v[174:177], v[10:13]
	v_mfma_i32_16x16x64_i8 v[114:117], v[134:137], v[182:185], v[114:117]
	v_mfma_i32_16x16x64_i8 v[106:109], v[142:145], v[182:185], v[106:109]
	v_mfma_i32_16x16x64_i8 v[86:89], v[134:137], v[190:193], v[86:89]
	v_mfma_i32_16x16x64_i8 v[82:85], v[142:145], v[190:193], v[82:85]
	v_mfma_i32_16x16x64_i8 v[50:53], v[146:149], v[162:165], v[50:53]
	v_mfma_i32_16x16x64_i8 v[6:9], v[154:157], v[162:165], v[6:9]
	v_mfma_i32_16x16x64_i8 v[42:45], v[146:149], v[170:173], v[42:45]
	v_mfma_i32_16x16x64_i8 v[2:5], v[154:157], v[170:173], v[2:5]
	v_mfma_i32_16x16x64_i8 v[54:57], v[146:149], v[178:181], v[54:57]
	v_mfma_i32_16x16x64_i8 v[46:49], v[154:157], v[178:181], v[46:49]
	v_mfma_i32_16x16x64_i8 v[38:41], v[146:149], v[186:189], v[38:41]
	v_mfma_i32_16x16x64_i8 v[34:37], v[154:157], v[186:189], v[34:37]
	v_mfma_i32_16x16x64_i8 v[50:53], v[150:153], v[166:169], v[50:53]
	v_mfma_i32_16x16x64_i8 v[6:9], v[158:161], v[166:169], v[6:9]
	v_mfma_i32_16x16x64_i8 v[42:45], v[150:153], v[174:177], v[42:45]
	v_mfma_i32_16x16x64_i8 v[2:5], v[158:161], v[174:177], v[2:5]
	s_barrier
	v_mfma_i32_16x16x64_i8 v[54:57], v[150:153], v[182:185], v[54:57]
	v_mfma_i32_16x16x64_i8 v[46:49], v[158:161], v[182:185], v[46:49]
	v_mfma_i32_16x16x64_i8 v[38:41], v[150:153], v[190:193], v[38:41]
	v_mfma_i32_16x16x64_i8 v[34:37], v[158:161], v[190:193], v[34:37]
	s_setprio 0
	s_add_i32 s92, s92, 2
	s_add_u32 s90, s90, 0x100
	s_addc_u32 s91, s91, 0
	s_cmp_gt_u32 s92, 29
	s_mov_b64 s[2:3], s[56:57]
	s_cbranch_scc0 .LBB0_845
	s_and_b64 vcc, exec, s[38:39]
	s_cbranch_vccz .LBB0_848
	s_barrier

.LBB0_1099:
	ds_read_b128 v[130:133], v167
	ds_read_b128 v[134:137], v167 offset:1024
	ds_read_b128 v[138:141], v167 offset:2048
	ds_read_b128 v[142:145], v167 offset:3072
	ds_read_b128 v[170:173], v168
	ds_read_b128 v[174:177], v168 offset:1024
	ds_read_b128 v[178:181], v168 offset:2048
	ds_read_b128 v[182:185], v168 offset:3072
	s_add_u32 s30, s28, 0x100
	s_addc_u32 s31, s29, 0
	s_cmpk_eq_i32 s72, 0x52
	s_cselect_b32 s37, s3, s31
	s_cselect_b32 s36, s2, s30
	s_cselect_b32 s35, s27, s71
	s_cselect_b32 s34, s26, s70
	v_lshl_add_u64 v[162:163], s[28:29], 0, v[154:155]
	s_add_i32 m0, s47, 0xc000
	ds_read_b128 v[186:189], v169
	ds_read_b128 v[190:193], v169 offset:1024
	ds_read_b128 v[194:197], v169 offset:2048
	ds_read_b128 v[198:201], v169 offset:3072
	ds_read_b128 v[202:205], v169 offset:4096
	ds_read_b128 v[206:209], v169 offset:5120
	ds_read_b128 v[210:213], v169 offset:6144
	ds_read_b128 v[214:217], v169 offset:7168
	global_load_lds_dwordx4 v[162:163], off
	v_lshl_add_u64 v[162:163], s[28:29], 0, v[156:157]
	s_add_i32 m0, s47, 0xe000
	s_nop 0
	global_load_lds_dwordx4 v[162:163], off
	s_waitcnt vmcnt(8)
	s_waitcnt lgkmcnt(0)
	s_setprio 1
	s_barrier
	v_mfma_i32_16x16x64_i8 v[126:129], v[130:133], v[186:189], v[126:129]
	v_mfma_i32_16x16x64_i8 v[122:125], v[138:141], v[186:189], v[122:125]
	v_mfma_i32_16x16x64_i8 v[110:113], v[130:133], v[194:197], v[110:113]
	v_mfma_i32_16x16x64_i8 v[106:109], v[138:141], v[194:197], v[106:109]
	v_mfma_i32_16x16x64_i8 v[94:97], v[130:133], v[202:205], v[94:97]
	v_mfma_i32_16x16x64_i8 v[90:93], v[138:141], v[202:205], v[90:93]
	v_mfma_i32_16x16x64_i8 v[78:81], v[130:133], v[210:213], v[78:81]
	v_mfma_i32_16x16x64_i8 v[74:77], v[138:141], v[210:213], v[74:77]
	v_mfma_i32_16x16x64_i8 v[126:129], v[134:137], v[190:193], v[126:129]
	v_mfma_i32_16x16x64_i8 v[122:125], v[142:145], v[190:193], v[122:125]
	v_mfma_i32_16x16x64_i8 v[110:113], v[134:137], v[198:201], v[110:113]
	v_mfma_i32_16x16x64_i8 v[106:109], v[142:145], v[198:201], v[106:109]
	v_mfma_i32_16x16x64_i8 v[94:97], v[134:137], v[206:209], v[94:97]
	v_mfma_i32_16x16x64_i8 v[90:93], v[142:145], v[206:209], v[90:93]
	v_mfma_i32_16x16x64_i8 v[78:81], v[134:137], v[214:217], v[78:81]
	v_mfma_i32_16x16x64_i8 v[74:77], v[142:145], v[214:217], v[74:77]
	v_mfma_i32_16x16x64_i8 v[118:121], v[170:173], v[186:189], v[118:121]
	v_mfma_i32_16x16x64_i8 v[114:117], v[178:181], v[186:189], v[114:117]
	v_mfma_i32_16x16x64_i8 v[102:105], v[170:173], v[194:197], v[102:105]
	v_mfma_i32_16x16x64_i8 v[98:101], v[178:181], v[194:197], v[98:101]
	v_mfma_i32_16x16x64_i8 v[86:89], v[170:173], v[202:205], v[86:89]
	v_mfma_i32_16x16x64_i8 v[82:85], v[178:181], v[202:205], v[82:85]
	v_mfma_i32_16x16x64_i8 v[70:73], v[170:173], v[210:213], v[70:73]
	v_mfma_i32_16x16x64_i8 v[66:69], v[178:181], v[210:213], v[66:69]
	v_mfma_i32_16x16x64_i8 v[118:121], v[174:177], v[190:193], v[118:121]
	v_mfma_i32_16x16x64_i8 v[114:117], v[182:185], v[190:193], v[114:117]
	v_mfma_i32_16x16x64_i8 v[102:105], v[174:177], v[198:201], v[102:105]
	v_mfma_i32_16x16x64_i8 v[98:101], v[182:185], v[198:201], v[98:101]
	s_barrier
	v_mfma_i32_16x16x64_i8 v[86:89], v[174:177], v[206:209], v[86:89]
	v_mfma_i32_16x16x64_i8 v[82:85], v[182:185], v[206:209], v[82:85]
	v_mfma_i32_16x16x64_i8 v[70:73], v[174:177], v[214:217], v[70:73]
	v_mfma_i32_16x16x64_i8 v[66:69], v[182:185], v[214:217], v[66:69]
	s_setprio 0
	s_add_i32 s28, s56, s46
	v_lshl_add_u64 v[162:163], s[34:35], 0, v[150:151]
	s_mov_b32 m0, s28
	ds_read_b128 v[186:189], v169 offset:16384
	ds_read_b128 v[190:193], v169 offset:17408
	ds_read_b128 v[194:197], v169 offset:18432
	ds_read_b128 v[198:201], v169 offset:19456
	ds_read_b128 v[202:205], v169 offset:20480
	ds_read_b128 v[206:209], v169 offset:21504
	ds_read_b128 v[210:213], v169 offset:22528
	ds_read_b128 v[214:217], v169 offset:23552
	global_load_lds_dwordx4 v[162:163], off
	s_add_i32 m0, s28, 0x2000
	s_add_u32 s28, s34, 0x158000
	v_lshl_add_u64 v[218:219], s[34:35], 0, v[146:147]
	s_addc_u32 s29, s35, 0
	s_add_i32 s73, s57, s46
	global_load_lds_dwordx4 v[218:219], off
	v_lshl_add_u64 v[220:221], s[28:29], 0, v[150:151]
	s_mov_b32 m0, s73
	v_lshl_add_u64 v[222:223], s[36:37], 0, v[148:149]
	global_load_lds_dwordx4 v[220:221], off
	v_lshl_add_u64 v[220:221], s[28:29], 0, v[146:147]
	s_add_i32 m0, s73, 0x2000
	s_nop 0
	global_load_lds_dwordx4 v[220:221], off
	v_lshl_add_u64 v[220:221], s[36:37], 0, v[152:153]
	s_mov_b32 m0, s47
	s_nop 0
	global_load_lds_dwordx4 v[220:221], off
	s_mov_b32 m0, s48
	s_nop 0
	global_load_lds_dwordx4 v[222:223], off
	s_waitcnt vmcnt(8)
	s_waitcnt lgkmcnt(0)
	s_setprio 1
	s_barrier
	v_mfma_i32_16x16x64_i8 v[62:65], v[130:133], v[186:189], v[62:65]
	v_mfma_i32_16x16x64_i8 v[58:61], v[138:141], v[186:189], v[58:61]
	v_mfma_i32_16x16x64_i8 v[46:49], v[130:133], v[194:197], v[46:49]
	v_mfma_i32_16x16x64_i8 v[42:45], v[138:141], v[194:197], v[42:45]
	v_mfma_i32_16x16x64_i8 v[30:33], v[130:133], v[202:205], v[30:33]
	v_mfma_i32_16x16x64_i8 v[26:29], v[138:141], v[202:205], v[26:29]
	v_mfma_i32_16x16x64_i8 v[14:17], v[130:133], v[210:213], v[14:17]
	v_mfma_i32_16x16x64_i8 v[10:13], v[138:141], v[210:213], v[10:13]
	v_mfma_i32_16x16x64_i8 v[62:65], v[134:137], v[190:193], v[62:65]
	v_mfma_i32_16x16x64_i8 v[58:61], v[142:145], v[190:193], v[58:61]
	v_mfma_i32_16x16x64_i8 v[46:49], v[134:137], v[198:201], v[46:49]
	v_mfma_i32_16x16x64_i8 v[42:45], v[142:145], v[198:201], v[42:45]
	v_mfma_i32_16x16x64_i8 v[30:33], v[134:137], v[206:209], v[30:33]
	v_mfma_i32_16x16x64_i8 v[26:29], v[142:145], v[206:209], v[26:29]
	v_mfma_i32_16x16x64_i8 v[14:17], v[134:137], v[214:217], v[14:17]
	v_mfma_i32_16x16x64_i8 v[10:13], v[142:145], v[214:217], v[10:13]
	v_mfma_i32_16x16x64_i8 v[54:57], v[170:173], v[186:189], v[54:57]
	v_mfma_i32_16x16x64_i8 v[50:53], v[178:181], v[186:189], v[50:53]
	v_mfma_i32_16x16x64_i8 v[38:41], v[170:173], v[194:197], v[38:41]
	v_mfma_i32_16x16x64_i8 v[34:37], v[178:181], v[194:197], v[34:37]
	v_mfma_i32_16x16x64_i8 v[22:25], v[170:173], v[202:205], v[22:25]
	v_mfma_i32_16x16x64_i8 v[18:21], v[178:181], v[202:205], v[18:21]
	v_mfma_i32_16x16x64_i8 v[6:9], v[170:173], v[210:213], v[6:9]
	v_mfma_i32_16x16x64_i8 v[2:5], v[178:181], v[210:213], v[2:5]
	v_mfma_i32_16x16x64_i8 v[54:57], v[174:177], v[190:193], v[54:57]
	v_mfma_i32_16x16x64_i8 v[50:53], v[182:185], v[190:193], v[50:53]
	v_mfma_i32_16x16x64_i8 v[38:41], v[174:177], v[198:201], v[38:41]
	v_mfma_i32_16x16x64_i8 v[34:37], v[182:185], v[198:201], v[34:37]
	s_barrier
	v_mfma_i32_16x16x64_i8 v[22:25], v[174:177], v[206:209], v[22:25]
	v_mfma_i32_16x16x64_i8 v[18:21], v[182:185], v[206:209], v[18:21]
	v_mfma_i32_16x16x64_i8 v[6:9], v[174:177], v[214:217], v[6:9]
	v_mfma_i32_16x16x64_i8 v[2:5], v[182:185], v[214:217], v[2:5]
	s_setprio 0
	s_add_i32 s73, 0, 0x18000
	s_add_i32 s74, 0, 0x1c000
	v_add_u32_e32 v142, s73, v166
	v_add_u32_e32 v182, s74, v166
	ds_read_b128 v[130:133], v142
	ds_read_b128 v[134:137], v142 offset:1024
	ds_read_b128 v[138:141], v142 offset:2048
	ds_read_b128 v[142:145], v142 offset:3072
	ds_read_b128 v[170:173], v182
	ds_read_b128 v[174:177], v182 offset:1024
	ds_read_b128 v[178:181], v182 offset:2048
	ds_read_b128 v[182:185], v182 offset:3072
	s_add_u32 s28, s36, 0x158000
	s_addc_u32 s29, s37, 0
	s_mov_b32 m0, s49
	v_lshl_add_u64 v[224:225], s[28:29], 0, v[152:153]
	ds_read_b128 v[186:189], v169 offset:32768
	ds_read_b128 v[190:193], v169 offset:33792
	ds_read_b128 v[194:197], v169 offset:34816
	ds_read_b128 v[198:201], v169 offset:35840
	ds_read_b128 v[202:205], v169 offset:36864
	ds_read_b128 v[206:209], v169 offset:37888
	ds_read_b128 v[210:213], v169 offset:38912
	ds_read_b128 v[214:217], v169 offset:39936
	global_load_lds_dwordx4 v[224:225], off
	v_lshl_add_u64 v[224:225], s[28:29], 0, v[148:149]
	s_mov_b32 m0, s50
	s_nop 0
	global_load_lds_dwordx4 v[224:225], off
	s_waitcnt vmcnt(8)
	s_waitcnt lgkmcnt(0)
	s_setprio 1
	s_barrier
	v_mfma_i32_16x16x64_i8 v[126:129], v[130:133], v[186:189], v[126:129]
	v_mfma_i32_16x16x64_i8 v[122:125], v[138:141], v[186:189], v[122:125]
	v_mfma_i32_16x16x64_i8 v[110:113], v[130:133], v[194:197], v[110:113]
	v_mfma_i32_16x16x64_i8 v[106:109], v[138:141], v[194:197], v[106:109]
	v_mfma_i32_16x16x64_i8 v[94:97], v[130:133], v[202:205], v[94:97]
	v_mfma_i32_16x16x64_i8 v[90:93], v[138:141], v[202:205], v[90:93]
	v_mfma_i32_16x16x64_i8 v[78:81], v[130:133], v[210:213], v[78:81]
	v_mfma_i32_16x16x64_i8 v[74:77], v[138:141], v[210:213], v[74:77]
	v_mfma_i32_16x16x64_i8 v[126:129], v[134:137], v[190:193], v[126:129]
	v_mfma_i32_16x16x64_i8 v[122:125], v[142:145], v[190:193], v[122:125]
	v_mfma_i32_16x16x64_i8 v[110:113], v[134:137], v[198:201], v[110:113]
	v_mfma_i32_16x16x64_i8 v[106:109], v[142:145], v[198:201], v[106:109]
	v_mfma_i32_16x16x64_i8 v[94:97], v[134:137], v[206:209], v[94:97]
	v_mfma_i32_16x16x64_i8 v[90:93], v[142:145], v[206:209], v[90:93]
	v_mfma_i32_16x16x64_i8 v[78:81], v[134:137], v[214:217], v[78:81]
	v_mfma_i32_16x16x64_i8 v[74:77], v[142:145], v[214:217], v[74:77]
	v_mfma_i32_16x16x64_i8 v[118:121], v[170:173], v[186:189], v[118:121]
	v_mfma_i32_16x16x64_i8 v[114:117], v[178:181], v[186:189], v[114:117]
	v_mfma_i32_16x16x64_i8 v[102:105], v[170:173], v[194:197], v[102:105]
	v_mfma_i32_16x16x64_i8 v[98:101], v[178:181], v[194:197], v[98:101]
	v_mfma_i32_16x16x64_i8 v[86:89], v[170:173], v[202:205], v[86:89]
	v_mfma_i32_16x16x64_i8 v[82:85], v[178:181], v[202:205], v[82:85]
	v_mfma_i32_16x16x64_i8 v[70:73], v[170:173], v[210:213], v[70:73]
	v_mfma_i32_16x16x64_i8 v[66:69], v[178:181], v[210:213], v[66:69]
	v_mfma_i32_16x16x64_i8 v[118:121], v[174:177], v[190:193], v[118:121]
	v_mfma_i32_16x16x64_i8 v[114:117], v[182:185], v[190:193], v[114:117]
	v_mfma_i32_16x16x64_i8 v[102:105], v[174:177], v[198:201], v[102:105]
	v_mfma_i32_16x16x64_i8 v[98:101], v[182:185], v[198:201], v[98:101]
	s_barrier
	v_mfma_i32_16x16x64_i8 v[86:89], v[174:177], v[206:209], v[86:89]
	v_mfma_i32_16x16x64_i8 v[82:85], v[182:185], v[206:209], v[82:85]
	v_mfma_i32_16x16x64_i8 v[70:73], v[174:177], v[214:217], v[70:73]
	v_mfma_i32_16x16x64_i8 v[66:69], v[182:185], v[214:217], v[66:69]
	s_setprio 0
	s_add_i32 s28, s73, s46
	v_lshl_add_u64 v[162:163], v[162:163], 0, s[14:15]
	s_mov_b32 m0, s28
	ds_read_b128 v[186:189], v169 offset:49152
	ds_read_b128 v[190:193], v169 offset:50176
	ds_read_b128 v[194:197], v169 offset:51200
	ds_read_b128 v[198:201], v169 offset:52224
	ds_read_b128 v[202:205], v169 offset:53248
	ds_read_b128 v[206:209], v169 offset:54272
	ds_read_b128 v[210:213], v169 offset:55296
	ds_read_b128 v[214:217], v169 offset:56320
	global_load_lds_dwordx4 v[162:163], off
	s_add_i32 m0, s28, 0x2000
	s_add_u32 s28, s34, 0x158080
	v_lshl_add_u64 v[162:163], v[218:219], 0, s[14:15]
	s_addc_u32 s29, s35, 0
	s_add_i32 s34, s74, s46
	global_load_lds_dwordx4 v[162:163], off
	v_lshl_add_u64 v[162:163], s[28:29], 0, v[150:151]
	s_mov_b32 m0, s34
	s_nop 0
	global_load_lds_dwordx4 v[162:163], off
	v_lshl_add_u64 v[162:163], s[28:29], 0, v[146:147]
	s_add_i32 m0, s34, 0x2000
	s_nop 0
	global_load_lds_dwordx4 v[162:163], off
	v_lshl_add_u64 v[162:163], v[220:221], 0, s[14:15]
	s_mov_b32 m0, s54
	s_nop 0
	global_load_lds_dwordx4 v[162:163], off
	v_lshl_add_u64 v[162:163], v[222:223], 0, s[14:15]
	s_mov_b32 m0, s55
	s_nop 0
	global_load_lds_dwordx4 v[162:163], off
	s_waitcnt vmcnt(8)
	s_waitcnt lgkmcnt(0)
	s_setprio 1
	s_barrier
	v_mfma_i32_16x16x64_i8 v[62:65], v[130:133], v[186:189], v[62:65]
	v_mfma_i32_16x16x64_i8 v[58:61], v[138:141], v[186:189], v[58:61]
	v_mfma_i32_16x16x64_i8 v[46:49], v[130:133], v[194:197], v[46:49]
	v_mfma_i32_16x16x64_i8 v[42:45], v[138:141], v[194:197], v[42:45]
	v_mfma_i32_16x16x64_i8 v[30:33], v[130:133], v[202:205], v[30:33]
	v_mfma_i32_16x16x64_i8 v[26:29], v[138:141], v[202:205], v[26:29]
	v_mfma_i32_16x16x64_i8 v[14:17], v[130:133], v[210:213], v[14:17]
	v_mfma_i32_16x16x64_i8 v[10:13], v[138:141], v[210:213], v[10:13]
	v_mfma_i32_16x16x64_i8 v[62:65], v[134:137], v[190:193], v[62:65]
	v_mfma_i32_16x16x64_i8 v[58:61], v[142:145], v[190:193], v[58:61]
	v_mfma_i32_16x16x64_i8 v[46:49], v[134:137], v[198:201], v[46:49]
	v_mfma_i32_16x16x64_i8 v[42:45], v[142:145], v[198:201], v[42:45]
	v_mfma_i32_16x16x64_i8 v[30:33], v[134:137], v[206:209], v[30:33]
	v_mfma_i32_16x16x64_i8 v[26:29], v[142:145], v[206:209], v[26:29]
	v_mfma_i32_16x16x64_i8 v[14:17], v[134:137], v[214:217], v[14:17]
	v_mfma_i32_16x16x64_i8 v[10:13], v[142:145], v[214:217], v[10:13]
	v_mfma_i32_16x16x64_i8 v[54:57], v[170:173], v[186:189], v[54:57]
	v_mfma_i32_16x16x64_i8 v[50:53], v[178:181], v[186:189], v[50:53]
	v_mfma_i32_16x16x64_i8 v[38:41], v[170:173], v[194:197], v[38:41]
	v_mfma_i32_16x16x64_i8 v[34:37], v[178:181], v[194:197], v[34:37]
	v_mfma_i32_16x16x64_i8 v[22:25], v[170:173], v[202:205], v[22:25]
	v_mfma_i32_16x16x64_i8 v[18:21], v[178:181], v[202:205], v[18:21]
	v_mfma_i32_16x16x64_i8 v[6:9], v[170:173], v[210:213], v[6:9]
	v_mfma_i32_16x16x64_i8 v[2:5], v[178:181], v[210:213], v[2:5]
	v_mfma_i32_16x16x64_i8 v[54:57], v[174:177], v[190:193], v[54:57]
	v_mfma_i32_16x16x64_i8 v[50:53], v[182:185], v[190:193], v[50:53]
	v_mfma_i32_16x16x64_i8 v[38:41], v[174:177], v[198:201], v[38:41]
	v_mfma_i32_16x16x64_i8 v[34:37], v[182:185], v[198:201], v[34:37]
	s_barrier
	v_mfma_i32_16x16x64_i8 v[22:25], v[174:177], v[206:209], v[22:25]
	v_mfma_i32_16x16x64_i8 v[18:21], v[182:185], v[206:209], v[18:21]
	v_mfma_i32_16x16x64_i8 v[6:9], v[174:177], v[214:217], v[6:9]
	v_mfma_i32_16x16x64_i8 v[2:5], v[182:185], v[214:217], v[2:5]
	s_setprio 0
	s_add_i32 s72, s72, 2
	s_add_u32 s70, s70, 0x100
	s_addc_u32 s71, s71, 0
	s_cmpk_gt_u32 s72, 0x53
	s_mov_b64 s[28:29], s[30:31]
	s_cbranch_scc0 .LBB0_1099
	s_and_b64 vcc, exec, s[16:17]
	s_cbranch_vccz .LBB0_1102
	s_barrier

.LBB0_1246:
	ds_read_b128 v[130:133], v193
	ds_read_b128 v[134:137], v193 offset:1024
	ds_read_b128 v[138:141], v193 offset:2048
	ds_read_b128 v[142:145], v193 offset:3072
	ds_read_b128 v[162:165], v194
	ds_read_b128 v[166:169], v194 offset:1024
	ds_read_b128 v[170:173], v194 offset:2048
	ds_read_b128 v[174:177], v194 offset:3072
	s_add_u32 s30, s28, 0xfff00080
	s_addc_u32 s31, s29, -1
	s_cmp_eq_u32 s68, 60
	s_cselect_b32 s35, s3, s31
	s_cselect_b32 s34, s23, s30
	s_cselect_b32 s31, s17, s65
	s_cselect_b32 s30, s62, s63
	v_lshl_add_u64 v[216:217], s[28:29], 0, v[154:155]
	s_add_i32 m0, s45, 0xc000
	ds_read_b128 v[178:181], v195
	ds_read_b128 v[182:185], v195 offset:1024
	ds_read_b128 v[186:189], v195 offset:2048
	ds_read_b128 v[196:199], v195 offset:3072
	ds_read_b128 v[200:203], v195 offset:4096
	ds_read_b128 v[204:207], v195 offset:5120
	ds_read_b128 v[208:211], v195 offset:6144
	ds_read_b128 v[212:215], v195 offset:7168
	global_load_lds_dwordx4 v[216:217], off
	v_lshl_add_u64 v[216:217], s[28:29], 0, v[156:157]
	s_add_i32 m0, s45, 0xe000
	s_nop 0
	global_load_lds_dwordx4 v[216:217], off
	s_waitcnt vmcnt(8)
	s_waitcnt lgkmcnt(0)
	s_setprio 1
	s_barrier
	v_mfma_f32_16x16x32_bf16 v[126:129], v[130:133], v[178:181], v[126:129]
	v_mfma_f32_16x16x32_bf16 v[122:125], v[138:141], v[178:181], v[122:125]
	v_mfma_f32_16x16x32_bf16 v[118:121], v[130:133], v[186:189], v[118:121]
	v_mfma_f32_16x16x32_bf16 v[110:113], v[138:141], v[186:189], v[110:113]
	v_mfma_f32_16x16x32_bf16 v[98:101], v[130:133], v[200:203], v[98:101]
	v_mfma_f32_16x16x32_bf16 v[90:93], v[138:141], v[200:203], v[90:93]
	v_mfma_f32_16x16x32_bf16 v[82:85], v[130:133], v[208:211], v[82:85]
	v_mfma_f32_16x16x32_bf16 v[74:77], v[138:141], v[208:211], v[74:77]
	v_mfma_f32_16x16x32_bf16 v[126:129], v[134:137], v[182:185], v[126:129]
	v_mfma_f32_16x16x32_bf16 v[122:125], v[142:145], v[182:185], v[122:125]
	v_mfma_f32_16x16x32_bf16 v[118:121], v[134:137], v[196:199], v[118:121]
	v_mfma_f32_16x16x32_bf16 v[110:113], v[142:145], v[196:199], v[110:113]
	v_mfma_f32_16x16x32_bf16 v[98:101], v[134:137], v[204:207], v[98:101]
	v_mfma_f32_16x16x32_bf16 v[90:93], v[142:145], v[204:207], v[90:93]
	v_mfma_f32_16x16x32_bf16 v[82:85], v[134:137], v[212:215], v[82:85]
	v_mfma_f32_16x16x32_bf16 v[74:77], v[142:145], v[212:215], v[74:77]
	v_mfma_f32_16x16x32_bf16 v[114:117], v[162:165], v[178:181], v[114:117]
	v_mfma_f32_16x16x32_bf16 v[106:109], v[170:173], v[178:181], v[106:109]
	v_mfma_f32_16x16x32_bf16 v[102:105], v[162:165], v[186:189], v[102:105]
	v_mfma_f32_16x16x32_bf16 v[94:97], v[170:173], v[186:189], v[94:97]
	v_mfma_f32_16x16x32_bf16 v[86:89], v[162:165], v[200:203], v[86:89]
	v_mfma_f32_16x16x32_bf16 v[78:81], v[170:173], v[200:203], v[78:81]
	v_mfma_f32_16x16x32_bf16 v[70:73], v[162:165], v[208:211], v[70:73]
	v_mfma_f32_16x16x32_bf16 v[66:69], v[170:173], v[208:211], v[66:69]
	v_mfma_f32_16x16x32_bf16 v[114:117], v[166:169], v[182:185], v[114:117]
	v_mfma_f32_16x16x32_bf16 v[106:109], v[174:177], v[182:185], v[106:109]
	v_mfma_f32_16x16x32_bf16 v[102:105], v[166:169], v[196:199], v[102:105]
	v_mfma_f32_16x16x32_bf16 v[94:97], v[174:177], v[196:199], v[94:97]
	s_barrier
	v_mfma_f32_16x16x32_bf16 v[86:89], v[166:169], v[204:207], v[86:89]
	v_mfma_f32_16x16x32_bf16 v[78:81], v[174:177], v[204:207], v[78:81]
	v_mfma_f32_16x16x32_bf16 v[70:73], v[166:169], v[212:215], v[70:73]
	v_mfma_f32_16x16x32_bf16 v[66:69], v[174:177], v[212:215], v[66:69]
	s_setprio 0
	s_add_i32 s69, s58, s44
	v_lshl_add_u64 v[216:217], s[30:31], 0, v[148:149]
	s_mov_b32 m0, s69
	ds_read_b128 v[178:181], v195 offset:16384
	ds_read_b128 v[182:185], v195 offset:17408
	ds_read_b128 v[186:189], v195 offset:18432
	ds_read_b128 v[196:199], v195 offset:19456
	ds_read_b128 v[200:203], v195 offset:20480
	ds_read_b128 v[204:207], v195 offset:21504
	ds_read_b128 v[208:211], v195 offset:22528
	ds_read_b128 v[212:215], v195 offset:23552
	global_load_lds_dwordx4 v[216:217], off
	s_add_i32 m0, s69, 0x2000
	s_add_u32 s70, s30, 0x100000
	v_lshl_add_u64 v[218:219], s[30:31], 0, v[152:153]
	s_addc_u32 s71, s31, 0
	s_add_i32 s69, s59, s44
	global_load_lds_dwordx4 v[218:219], off
	v_lshl_add_u64 v[220:221], s[70:71], 0, v[148:149]
	s_mov_b32 m0, s69
	v_lshl_add_u64 v[222:223], s[34:35], 0, v[150:151]
	global_load_lds_dwordx4 v[220:221], off
	v_lshl_add_u64 v[220:221], s[70:71], 0, v[152:153]
	s_add_i32 m0, s69, 0x2000
	s_nop 0
	global_load_lds_dwordx4 v[220:221], off
	v_lshl_add_u64 v[220:221], s[34:35], 0, v[146:147]
	s_mov_b32 m0, s45
	s_nop 0
	global_load_lds_dwordx4 v[220:221], off
	s_mov_b32 m0, s46
	s_nop 0
	global_load_lds_dwordx4 v[222:223], off
	s_waitcnt vmcnt(8)
	s_waitcnt lgkmcnt(0)
	s_setprio 1
	s_barrier
	v_mfma_f32_16x16x32_bf16 v[62:65], v[130:133], v[178:181], v[62:65]
	v_mfma_f32_16x16x32_bf16 v[58:61], v[138:141], v[178:181], v[58:61]
	v_mfma_f32_16x16x32_bf16 v[46:49], v[130:133], v[186:189], v[46:49]
	v_mfma_f32_16x16x32_bf16 v[42:45], v[138:141], v[186:189], v[42:45]
	v_mfma_f32_16x16x32_bf16 v[30:33], v[130:133], v[200:203], v[30:33]
	v_mfma_f32_16x16x32_bf16 v[26:29], v[138:141], v[200:203], v[26:29]
	v_mfma_f32_16x16x32_bf16 v[14:17], v[130:133], v[208:211], v[14:17]
	v_mfma_f32_16x16x32_bf16 v[10:13], v[138:141], v[208:211], v[10:13]
	v_mfma_f32_16x16x32_bf16 v[62:65], v[134:137], v[182:185], v[62:65]
	v_mfma_f32_16x16x32_bf16 v[58:61], v[142:145], v[182:185], v[58:61]
	v_mfma_f32_16x16x32_bf16 v[46:49], v[134:137], v[196:199], v[46:49]
	v_mfma_f32_16x16x32_bf16 v[42:45], v[142:145], v[196:199], v[42:45]
	v_mfma_f32_16x16x32_bf16 v[30:33], v[134:137], v[204:207], v[30:33]
	v_mfma_f32_16x16x32_bf16 v[26:29], v[142:145], v[204:207], v[26:29]
	v_mfma_f32_16x16x32_bf16 v[14:17], v[134:137], v[212:215], v[14:17]
	v_mfma_f32_16x16x32_bf16 v[10:13], v[142:145], v[212:215], v[10:13]
	v_mfma_f32_16x16x32_bf16 v[54:57], v[162:165], v[178:181], v[54:57]
	v_mfma_f32_16x16x32_bf16 v[50:53], v[170:173], v[178:181], v[50:53]
	v_mfma_f32_16x16x32_bf16 v[38:41], v[162:165], v[186:189], v[38:41]
	v_mfma_f32_16x16x32_bf16 v[34:37], v[170:173], v[186:189], v[34:37]
	v_mfma_f32_16x16x32_bf16 v[22:25], v[162:165], v[200:203], v[22:25]
	v_mfma_f32_16x16x32_bf16 v[18:21], v[170:173], v[200:203], v[18:21]
	v_mfma_f32_16x16x32_bf16 v[6:9], v[162:165], v[208:211], v[6:9]
	v_mfma_f32_16x16x32_bf16 v[2:5], v[170:173], v[208:211], v[2:5]
	v_mfma_f32_16x16x32_bf16 v[54:57], v[166:169], v[182:185], v[54:57]
	v_mfma_f32_16x16x32_bf16 v[50:53], v[174:177], v[182:185], v[50:53]
	v_mfma_f32_16x16x32_bf16 v[38:41], v[166:169], v[196:199], v[38:41]
	v_mfma_f32_16x16x32_bf16 v[34:37], v[174:177], v[196:199], v[34:37]
	s_barrier
	v_mfma_f32_16x16x32_bf16 v[22:25], v[166:169], v[204:207], v[22:25]
	v_mfma_f32_16x16x32_bf16 v[18:21], v[174:177], v[204:207], v[18:21]
	v_mfma_f32_16x16x32_bf16 v[6:9], v[166:169], v[212:215], v[6:9]
	v_mfma_f32_16x16x32_bf16 v[2:5], v[174:177], v[212:215], v[2:5]
	s_setprio 0
	s_add_i32 s69, 0, 0x18000
	s_add_i32 s70, 0, 0x1c000
	v_add_u32_e32 v142, s69, v192
	v_add_u32_e32 v174, s70, v192
	ds_read_b128 v[130:133], v142
	ds_read_b128 v[134:137], v142 offset:1024
	ds_read_b128 v[138:141], v142 offset:2048
	ds_read_b128 v[142:145], v142 offset:3072
	ds_read_b128 v[162:165], v174
	ds_read_b128 v[166:169], v174 offset:1024
	ds_read_b128 v[170:173], v174 offset:2048
	ds_read_b128 v[174:177], v174 offset:3072
	s_add_u32 s34, s34, 0x100000
	s_addc_u32 s35, s35, 0
	s_mov_b32 m0, s47
	v_lshl_add_u64 v[224:225], s[34:35], 0, v[146:147]
	ds_read_b128 v[178:181], v195 offset:32768
	ds_read_b128 v[182:185], v195 offset:33792
	ds_read_b128 v[186:189], v195 offset:34816
	ds_read_b128 v[196:199], v195 offset:35840
	ds_read_b128 v[200:203], v195 offset:36864
	ds_read_b128 v[204:207], v195 offset:37888
	ds_read_b128 v[208:211], v195 offset:38912
	ds_read_b128 v[212:215], v195 offset:39936
	global_load_lds_dwordx4 v[224:225], off
	v_lshl_add_u64 v[224:225], s[34:35], 0, v[150:151]
	s_mov_b32 m0, s48
	s_nop 0
	global_load_lds_dwordx4 v[224:225], off
	s_waitcnt vmcnt(8)
	s_waitcnt lgkmcnt(0)
	s_setprio 1
	s_barrier
	v_mfma_f32_16x16x32_bf16 v[126:129], v[130:133], v[178:181], v[126:129]
	v_mfma_f32_16x16x32_bf16 v[122:125], v[138:141], v[178:181], v[122:125]
	v_mfma_f32_16x16x32_bf16 v[118:121], v[130:133], v[186:189], v[118:121]
	v_mfma_f32_16x16x32_bf16 v[110:113], v[138:141], v[186:189], v[110:113]
	v_mfma_f32_16x16x32_bf16 v[98:101], v[130:133], v[200:203], v[98:101]
	v_mfma_f32_16x16x32_bf16 v[90:93], v[138:141], v[200:203], v[90:93]
	v_mfma_f32_16x16x32_bf16 v[82:85], v[130:133], v[208:211], v[82:85]
	v_mfma_f32_16x16x32_bf16 v[74:77], v[138:141], v[208:211], v[74:77]
	v_mfma_f32_16x16x32_bf16 v[126:129], v[134:137], v[182:185], v[126:129]
	v_mfma_f32_16x16x32_bf16 v[122:125], v[142:145], v[182:185], v[122:125]
	v_mfma_f32_16x16x32_bf16 v[118:121], v[134:137], v[196:199], v[118:121]
	v_mfma_f32_16x16x32_bf16 v[110:113], v[142:145], v[196:199], v[110:113]
	v_mfma_f32_16x16x32_bf16 v[98:101], v[134:137], v[204:207], v[98:101]
	v_mfma_f32_16x16x32_bf16 v[90:93], v[142:145], v[204:207], v[90:93]
	v_mfma_f32_16x16x32_bf16 v[82:85], v[134:137], v[212:215], v[82:85]
	v_mfma_f32_16x16x32_bf16 v[74:77], v[142:145], v[212:215], v[74:77]
	v_mfma_f32_16x16x32_bf16 v[114:117], v[162:165], v[178:181], v[114:117]
	v_mfma_f32_16x16x32_bf16 v[106:109], v[170:173], v[178:181], v[106:109]
	v_mfma_f32_16x16x32_bf16 v[102:105], v[162:165], v[186:189], v[102:105]
	v_mfma_f32_16x16x32_bf16 v[94:97], v[170:173], v[186:189], v[94:97]
	v_mfma_f32_16x16x32_bf16 v[86:89], v[162:165], v[200:203], v[86:89]
	v_mfma_f32_16x16x32_bf16 v[78:81], v[170:173], v[200:203], v[78:81]
	v_mfma_f32_16x16x32_bf16 v[70:73], v[162:165], v[208:211], v[70:73]
	v_mfma_f32_16x16x32_bf16 v[66:69], v[170:173], v[208:211], v[66:69]
	v_mfma_f32_16x16x32_bf16 v[114:117], v[166:169], v[182:185], v[114:117]
	v_mfma_f32_16x16x32_bf16 v[106:109], v[174:177], v[182:185], v[106:109]
	v_mfma_f32_16x16x32_bf16 v[102:105], v[166:169], v[196:199], v[102:105]
	v_mfma_f32_16x16x32_bf16 v[94:97], v[174:177], v[196:199], v[94:97]
	s_barrier
	v_mfma_f32_16x16x32_bf16 v[86:89], v[166:169], v[204:207], v[86:89]
	v_mfma_f32_16x16x32_bf16 v[78:81], v[174:177], v[204:207], v[78:81]
	v_mfma_f32_16x16x32_bf16 v[70:73], v[166:169], v[212:215], v[70:73]
	v_mfma_f32_16x16x32_bf16 v[66:69], v[174:177], v[212:215], v[66:69]
	s_setprio 0
	s_add_i32 s34, s69, s44
	v_lshl_add_u64 v[216:217], v[216:217], 0, s[12:13]
	s_mov_b32 m0, s34
	ds_read_b128 v[178:181], v195 offset:49152
	ds_read_b128 v[182:185], v195 offset:50176
	ds_read_b128 v[186:189], v195 offset:51200
	ds_read_b128 v[196:199], v195 offset:52224
	ds_read_b128 v[200:203], v195 offset:53248
	ds_read_b128 v[204:207], v195 offset:54272
	ds_read_b128 v[208:211], v195 offset:55296
	ds_read_b128 v[212:215], v195 offset:56320
	global_load_lds_dwordx4 v[216:217], off
	s_add_i32 m0, s34, 0x2000
	s_add_u32 s30, s30, 0x100080
	v_lshl_add_u64 v[216:217], v[218:219], 0, s[12:13]
	s_addc_u32 s31, s31, 0
	s_add_i32 s34, s70, s44
	global_load_lds_dwordx4 v[216:217], off
	v_lshl_add_u64 v[216:217], s[30:31], 0, v[148:149]
	s_mov_b32 m0, s34
	s_nop 0
	global_load_lds_dwordx4 v[216:217], off
	v_lshl_add_u64 v[216:217], s[30:31], 0, v[152:153]
	s_add_i32 m0, s34, 0x2000
	s_nop 0
	global_load_lds_dwordx4 v[216:217], off
	v_lshl_add_u64 v[216:217], v[220:221], 0, s[12:13]
	s_mov_b32 m0, s55
	s_nop 0
	global_load_lds_dwordx4 v[216:217], off
	v_lshl_add_u64 v[216:217], v[222:223], 0, s[12:13]
	s_mov_b32 m0, s56
	s_nop 0
	global_load_lds_dwordx4 v[216:217], off
	s_waitcnt vmcnt(8)
	s_waitcnt lgkmcnt(0)
	s_setprio 1
	s_barrier
	v_mfma_f32_16x16x32_bf16 v[62:65], v[130:133], v[178:181], v[62:65]
	v_mfma_f32_16x16x32_bf16 v[58:61], v[138:141], v[178:181], v[58:61]
	v_mfma_f32_16x16x32_bf16 v[46:49], v[130:133], v[186:189], v[46:49]
	v_mfma_f32_16x16x32_bf16 v[42:45], v[138:141], v[186:189], v[42:45]
	v_mfma_f32_16x16x32_bf16 v[30:33], v[130:133], v[200:203], v[30:33]
	v_mfma_f32_16x16x32_bf16 v[26:29], v[138:141], v[200:203], v[26:29]
	v_mfma_f32_16x16x32_bf16 v[14:17], v[130:133], v[208:211], v[14:17]
	v_mfma_f32_16x16x32_bf16 v[10:13], v[138:141], v[208:211], v[10:13]
	v_mfma_f32_16x16x32_bf16 v[62:65], v[134:137], v[182:185], v[62:65]
	v_mfma_f32_16x16x32_bf16 v[58:61], v[142:145], v[182:185], v[58:61]
	v_mfma_f32_16x16x32_bf16 v[46:49], v[134:137], v[196:199], v[46:49]
	v_mfma_f32_16x16x32_bf16 v[42:45], v[142:145], v[196:199], v[42:45]
	v_mfma_f32_16x16x32_bf16 v[30:33], v[134:137], v[204:207], v[30:33]
	v_mfma_f32_16x16x32_bf16 v[26:29], v[142:145], v[204:207], v[26:29]
	v_mfma_f32_16x16x32_bf16 v[14:17], v[134:137], v[212:215], v[14:17]
	v_mfma_f32_16x16x32_bf16 v[10:13], v[142:145], v[212:215], v[10:13]
	v_mfma_f32_16x16x32_bf16 v[54:57], v[162:165], v[178:181], v[54:57]
	v_mfma_f32_16x16x32_bf16 v[50:53], v[170:173], v[178:181], v[50:53]
	v_mfma_f32_16x16x32_bf16 v[38:41], v[162:165], v[186:189], v[38:41]
	v_mfma_f32_16x16x32_bf16 v[34:37], v[170:173], v[186:189], v[34:37]
	v_mfma_f32_16x16x32_bf16 v[22:25], v[162:165], v[200:203], v[22:25]
	v_mfma_f32_16x16x32_bf16 v[18:21], v[170:173], v[200:203], v[18:21]
	v_mfma_f32_16x16x32_bf16 v[6:9], v[162:165], v[208:211], v[6:9]
	v_mfma_f32_16x16x32_bf16 v[2:5], v[170:173], v[208:211], v[2:5]
	v_mfma_f32_16x16x32_bf16 v[54:57], v[166:169], v[182:185], v[54:57]
	v_mfma_f32_16x16x32_bf16 v[50:53], v[174:177], v[182:185], v[50:53]
	v_mfma_f32_16x16x32_bf16 v[38:41], v[166:169], v[196:199], v[38:41]
	v_mfma_f32_16x16x32_bf16 v[34:37], v[174:177], v[196:199], v[34:37]
	s_barrier
	v_mfma_f32_16x16x32_bf16 v[22:25], v[166:169], v[204:207], v[22:25]
	v_mfma_f32_16x16x32_bf16 v[18:21], v[174:177], v[204:207], v[18:21]
	v_mfma_f32_16x16x32_bf16 v[6:9], v[166:169], v[212:215], v[6:9]
	v_mfma_f32_16x16x32_bf16 v[2:5], v[174:177], v[212:215], v[2:5]
	s_setprio 0
	s_add_i32 s68, s68, 2
	s_add_u32 s28, s28, 0x100
	s_addc_u32 s29, s29, 0
	s_add_u32 s63, s63, 0x100
	s_addc_u32 s65, s65, 0
	s_cmp_gt_u32 s68, 61
	s_cbranch_scc0 .LBB0_1246
	s_and_b64 vcc, exec, s[14:15]
	s_cbranch_vccz .LBB0_1249
	s_barrier

.LBB0_1521:
	ds_read_b128 v[130:133], v169
	ds_read_b128 v[134:137], v169 offset:1024
	ds_read_b128 v[138:141], v169 offset:2048
	ds_read_b128 v[142:145], v169 offset:3072
	ds_read_b128 v[162:165], v170
	ds_read_b128 v[172:175], v170 offset:1024
	ds_read_b128 v[176:179], v170 offset:2048
	ds_read_b128 v[180:183], v170 offset:3072
	s_add_u32 s38, s2, 0xfff00080
	s_addc_u32 s39, s3, -1
	s_cmp_eq_u32 s69, 60
	s_cselect_b32 s45, s29, s39
	s_cselect_b32 s44, s65, s38
	s_cselect_b32 s39, s27, s68
	s_cselect_b32 s38, s66, s67
	v_lshl_add_u64 v[216:217], s[2:3], 0, v[154:155]
	s_add_i32 m0, s37, 0xc000
	ds_read_b128 v[184:187], v171
	ds_read_b128 v[188:191], v171 offset:1024
	ds_read_b128 v[192:195], v171 offset:2048
	ds_read_b128 v[196:199], v171 offset:3072
	ds_read_b128 v[200:203], v171 offset:4096
	ds_read_b128 v[204:207], v171 offset:5120
	ds_read_b128 v[208:211], v171 offset:6144
	ds_read_b128 v[212:215], v171 offset:7168
	global_load_lds_dwordx4 v[216:217], off
	v_lshl_add_u64 v[216:217], s[2:3], 0, v[156:157]
	s_add_i32 m0, s37, 0xe000
	s_nop 0
	global_load_lds_dwordx4 v[216:217], off
	s_waitcnt vmcnt(8)
	s_waitcnt lgkmcnt(0)
	s_setprio 1
	s_barrier
	v_mfma_f32_16x16x32_bf16 v[126:129], v[130:133], v[184:187], v[126:129]
	v_mfma_f32_16x16x32_bf16 v[122:125], v[138:141], v[184:187], v[122:125]
	v_mfma_f32_16x16x32_bf16 v[114:117], v[130:133], v[192:195], v[114:117]
	v_mfma_f32_16x16x32_bf16 v[106:109], v[138:141], v[192:195], v[106:109]
	v_mfma_f32_16x16x32_bf16 v[98:101], v[130:133], v[200:203], v[98:101]
	v_mfma_f32_16x16x32_bf16 v[90:93], v[138:141], v[200:203], v[90:93]
	v_mfma_f32_16x16x32_bf16 v[82:85], v[130:133], v[208:211], v[82:85]
	v_mfma_f32_16x16x32_bf16 v[74:77], v[138:141], v[208:211], v[74:77]
	v_mfma_f32_16x16x32_bf16 v[126:129], v[134:137], v[188:191], v[126:129]
	v_mfma_f32_16x16x32_bf16 v[122:125], v[142:145], v[188:191], v[122:125]
	v_mfma_f32_16x16x32_bf16 v[114:117], v[134:137], v[196:199], v[114:117]
	v_mfma_f32_16x16x32_bf16 v[106:109], v[142:145], v[196:199], v[106:109]
	v_mfma_f32_16x16x32_bf16 v[98:101], v[134:137], v[204:207], v[98:101]
	v_mfma_f32_16x16x32_bf16 v[90:93], v[142:145], v[204:207], v[90:93]
	v_mfma_f32_16x16x32_bf16 v[82:85], v[134:137], v[212:215], v[82:85]
	v_mfma_f32_16x16x32_bf16 v[74:77], v[142:145], v[212:215], v[74:77]
	v_mfma_f32_16x16x32_bf16 v[118:121], v[162:165], v[184:187], v[118:121]
	v_mfma_f32_16x16x32_bf16 v[110:113], v[176:179], v[184:187], v[110:113]
	v_mfma_f32_16x16x32_bf16 v[102:105], v[162:165], v[192:195], v[102:105]
	v_mfma_f32_16x16x32_bf16 v[94:97], v[176:179], v[192:195], v[94:97]
	v_mfma_f32_16x16x32_bf16 v[86:89], v[162:165], v[200:203], v[86:89]
	v_mfma_f32_16x16x32_bf16 v[78:81], v[176:179], v[200:203], v[78:81]
	v_mfma_f32_16x16x32_bf16 v[70:73], v[162:165], v[208:211], v[70:73]
	v_mfma_f32_16x16x32_bf16 v[66:69], v[176:179], v[208:211], v[66:69]
	v_mfma_f32_16x16x32_bf16 v[118:121], v[172:175], v[188:191], v[118:121]
	v_mfma_f32_16x16x32_bf16 v[110:113], v[180:183], v[188:191], v[110:113]
	v_mfma_f32_16x16x32_bf16 v[102:105], v[172:175], v[196:199], v[102:105]
	v_mfma_f32_16x16x32_bf16 v[94:97], v[180:183], v[196:199], v[94:97]
	s_barrier
	v_mfma_f32_16x16x32_bf16 v[86:89], v[172:175], v[204:207], v[86:89]
	v_mfma_f32_16x16x32_bf16 v[78:81], v[180:183], v[204:207], v[78:81]
	v_mfma_f32_16x16x32_bf16 v[70:73], v[172:175], v[212:215], v[70:73]
	v_mfma_f32_16x16x32_bf16 v[66:69], v[180:183], v[212:215], v[66:69]
	s_setprio 0
	s_add_i32 s43, s57, s50
	v_lshl_add_u64 v[216:217], s[38:39], 0, v[150:151]
	s_mov_b32 m0, s43
	ds_read_b128 v[184:187], v171 offset:16384
	ds_read_b128 v[188:191], v171 offset:17408
	ds_read_b128 v[192:195], v171 offset:18432
	ds_read_b128 v[196:199], v171 offset:19456
	ds_read_b128 v[200:203], v171 offset:20480
	ds_read_b128 v[204:207], v171 offset:21504
	ds_read_b128 v[208:211], v171 offset:22528
	ds_read_b128 v[212:215], v171 offset:23552
	global_load_lds_dwordx4 v[216:217], off
	s_add_i32 m0, s43, 0x2000
	s_add_u32 s70, s38, 0x100000
	v_lshl_add_u64 v[218:219], s[38:39], 0, v[146:147]
	s_addc_u32 s71, s39, 0
	s_add_i32 s43, s58, s50
	global_load_lds_dwordx4 v[218:219], off
	v_lshl_add_u64 v[220:221], s[70:71], 0, v[150:151]
	s_mov_b32 m0, s43
	v_lshl_add_u64 v[222:223], s[44:45], 0, v[148:149]
	global_load_lds_dwordx4 v[220:221], off
	v_lshl_add_u64 v[220:221], s[70:71], 0, v[146:147]
	s_add_i32 m0, s43, 0x2000
	s_nop 0
	global_load_lds_dwordx4 v[220:221], off
	v_lshl_add_u64 v[220:221], s[44:45], 0, v[152:153]
	s_mov_b32 m0, s37
	s_nop 0
	global_load_lds_dwordx4 v[220:221], off
	s_mov_b32 m0, s51
	s_nop 0
	global_load_lds_dwordx4 v[222:223], off
	s_waitcnt vmcnt(8)
	s_waitcnt lgkmcnt(0)
	s_setprio 1
	s_barrier
	v_mfma_f32_16x16x32_bf16 v[62:65], v[130:133], v[184:187], v[62:65]
	v_mfma_f32_16x16x32_bf16 v[58:61], v[138:141], v[184:187], v[58:61]
	v_mfma_f32_16x16x32_bf16 v[50:53], v[130:133], v[192:195], v[50:53]
	v_mfma_f32_16x16x32_bf16 v[42:45], v[138:141], v[192:195], v[42:45]
	v_mfma_f32_16x16x32_bf16 v[34:37], v[130:133], v[200:203], v[34:37]
	v_mfma_f32_16x16x32_bf16 v[26:29], v[138:141], v[200:203], v[26:29]
	v_mfma_f32_16x16x32_bf16 v[18:21], v[130:133], v[208:211], v[18:21]
	v_mfma_f32_16x16x32_bf16 v[10:13], v[138:141], v[208:211], v[10:13]
	v_mfma_f32_16x16x32_bf16 v[62:65], v[134:137], v[188:191], v[62:65]
	v_mfma_f32_16x16x32_bf16 v[58:61], v[142:145], v[188:191], v[58:61]
	v_mfma_f32_16x16x32_bf16 v[50:53], v[134:137], v[196:199], v[50:53]
	v_mfma_f32_16x16x32_bf16 v[42:45], v[142:145], v[196:199], v[42:45]
	v_mfma_f32_16x16x32_bf16 v[34:37], v[134:137], v[204:207], v[34:37]
	v_mfma_f32_16x16x32_bf16 v[26:29], v[142:145], v[204:207], v[26:29]
	v_mfma_f32_16x16x32_bf16 v[18:21], v[134:137], v[212:215], v[18:21]
	v_mfma_f32_16x16x32_bf16 v[10:13], v[142:145], v[212:215], v[10:13]
	v_mfma_f32_16x16x32_bf16 v[54:57], v[162:165], v[184:187], v[54:57]
	v_mfma_f32_16x16x32_bf16 v[46:49], v[176:179], v[184:187], v[46:49]
	v_mfma_f32_16x16x32_bf16 v[38:41], v[162:165], v[192:195], v[38:41]
	v_mfma_f32_16x16x32_bf16 v[30:33], v[176:179], v[192:195], v[30:33]
	v_mfma_f32_16x16x32_bf16 v[22:25], v[162:165], v[200:203], v[22:25]
	v_mfma_f32_16x16x32_bf16 v[14:17], v[176:179], v[200:203], v[14:17]
	v_mfma_f32_16x16x32_bf16 v[6:9], v[162:165], v[208:211], v[6:9]
	v_mfma_f32_16x16x32_bf16 v[2:5], v[176:179], v[208:211], v[2:5]
	v_mfma_f32_16x16x32_bf16 v[54:57], v[172:175], v[188:191], v[54:57]
	v_mfma_f32_16x16x32_bf16 v[46:49], v[180:183], v[188:191], v[46:49]
	v_mfma_f32_16x16x32_bf16 v[38:41], v[172:175], v[196:199], v[38:41]
	v_mfma_f32_16x16x32_bf16 v[30:33], v[180:183], v[196:199], v[30:33]
	s_barrier
	v_mfma_f32_16x16x32_bf16 v[22:25], v[172:175], v[204:207], v[22:25]
	v_mfma_f32_16x16x32_bf16 v[14:17], v[180:183], v[204:207], v[14:17]
	v_mfma_f32_16x16x32_bf16 v[6:9], v[172:175], v[212:215], v[6:9]
	v_mfma_f32_16x16x32_bf16 v[2:5], v[180:183], v[212:215], v[2:5]
	s_setprio 0
	s_add_i32 s43, 0, 0x18000
	s_add_i32 s70, 0, 0x1c000
	v_add_u32_e32 v142, s43, v167
	v_add_u32_e32 v180, s70, v167
	ds_read_b128 v[130:133], v142
	ds_read_b128 v[134:137], v142 offset:1024
	ds_read_b128 v[138:141], v142 offset:2048
	ds_read_b128 v[142:145], v142 offset:3072
	ds_read_b128 v[162:165], v180
	ds_read_b128 v[172:175], v180 offset:1024
	ds_read_b128 v[176:179], v180 offset:2048
	ds_read_b128 v[180:183], v180 offset:3072
	s_add_u32 s44, s44, 0x100000
	s_addc_u32 s45, s45, 0
	s_mov_b32 m0, s52
	v_lshl_add_u64 v[224:225], s[44:45], 0, v[152:153]
	ds_read_b128 v[184:187], v171 offset:32768
	ds_read_b128 v[188:191], v171 offset:33792
	ds_read_b128 v[192:195], v171 offset:34816
	ds_read_b128 v[196:199], v171 offset:35840
	ds_read_b128 v[200:203], v171 offset:36864
	ds_read_b128 v[204:207], v171 offset:37888
	ds_read_b128 v[208:211], v171 offset:38912
	ds_read_b128 v[212:215], v171 offset:39936
	global_load_lds_dwordx4 v[224:225], off
	v_lshl_add_u64 v[224:225], s[44:45], 0, v[148:149]
	s_mov_b32 m0, s53
	s_nop 0
	global_load_lds_dwordx4 v[224:225], off
	s_waitcnt vmcnt(8)
	s_waitcnt lgkmcnt(0)
	s_setprio 1
	s_barrier
	v_mfma_f32_16x16x32_bf16 v[126:129], v[130:133], v[184:187], v[126:129]
	v_mfma_f32_16x16x32_bf16 v[122:125], v[138:141], v[184:187], v[122:125]
	v_mfma_f32_16x16x32_bf16 v[114:117], v[130:133], v[192:195], v[114:117]
	v_mfma_f32_16x16x32_bf16 v[106:109], v[138:141], v[192:195], v[106:109]
	v_mfma_f32_16x16x32_bf16 v[98:101], v[130:133], v[200:203], v[98:101]
	v_mfma_f32_16x16x32_bf16 v[90:93], v[138:141], v[200:203], v[90:93]
	v_mfma_f32_16x16x32_bf16 v[82:85], v[130:133], v[208:211], v[82:85]
	v_mfma_f32_16x16x32_bf16 v[74:77], v[138:141], v[208:211], v[74:77]
	v_mfma_f32_16x16x32_bf16 v[126:129], v[134:137], v[188:191], v[126:129]
	v_mfma_f32_16x16x32_bf16 v[122:125], v[142:145], v[188:191], v[122:125]
	v_mfma_f32_16x16x32_bf16 v[114:117], v[134:137], v[196:199], v[114:117]
	v_mfma_f32_16x16x32_bf16 v[106:109], v[142:145], v[196:199], v[106:109]
	v_mfma_f32_16x16x32_bf16 v[98:101], v[134:137], v[204:207], v[98:101]
	v_mfma_f32_16x16x32_bf16 v[90:93], v[142:145], v[204:207], v[90:93]
	v_mfma_f32_16x16x32_bf16 v[82:85], v[134:137], v[212:215], v[82:85]
	v_mfma_f32_16x16x32_bf16 v[74:77], v[142:145], v[212:215], v[74:77]
	v_mfma_f32_16x16x32_bf16 v[118:121], v[162:165], v[184:187], v[118:121]
	v_mfma_f32_16x16x32_bf16 v[110:113], v[176:179], v[184:187], v[110:113]
	v_mfma_f32_16x16x32_bf16 v[102:105], v[162:165], v[192:195], v[102:105]
	v_mfma_f32_16x16x32_bf16 v[94:97], v[176:179], v[192:195], v[94:97]
	v_mfma_f32_16x16x32_bf16 v[86:89], v[162:165], v[200:203], v[86:89]
	v_mfma_f32_16x16x32_bf16 v[78:81], v[176:179], v[200:203], v[78:81]
	v_mfma_f32_16x16x32_bf16 v[70:73], v[162:165], v[208:211], v[70:73]
	v_mfma_f32_16x16x32_bf16 v[66:69], v[176:179], v[208:211], v[66:69]
	v_mfma_f32_16x16x32_bf16 v[118:121], v[172:175], v[188:191], v[118:121]
	v_mfma_f32_16x16x32_bf16 v[110:113], v[180:183], v[188:191], v[110:113]
	v_mfma_f32_16x16x32_bf16 v[102:105], v[172:175], v[196:199], v[102:105]
	v_mfma_f32_16x16x32_bf16 v[94:97], v[180:183], v[196:199], v[94:97]
	s_barrier
	v_mfma_f32_16x16x32_bf16 v[86:89], v[172:175], v[204:207], v[86:89]
	v_mfma_f32_16x16x32_bf16 v[78:81], v[180:183], v[204:207], v[78:81]
	v_mfma_f32_16x16x32_bf16 v[70:73], v[172:175], v[212:215], v[70:73]
	v_mfma_f32_16x16x32_bf16 v[66:69], v[180:183], v[212:215], v[66:69]
	s_setprio 0
	s_add_i32 s43, s43, s50
	v_lshl_add_u64 v[216:217], v[216:217], 0, s[16:17]
	s_mov_b32 m0, s43
	ds_read_b128 v[184:187], v171 offset:49152
	ds_read_b128 v[188:191], v171 offset:50176
	ds_read_b128 v[192:195], v171 offset:51200
	ds_read_b128 v[196:199], v171 offset:52224
	ds_read_b128 v[200:203], v171 offset:53248
	ds_read_b128 v[204:207], v171 offset:54272
	ds_read_b128 v[208:211], v171 offset:55296
	ds_read_b128 v[212:215], v171 offset:56320
	global_load_lds_dwordx4 v[216:217], off
	s_add_i32 m0, s43, 0x2000
	s_add_u32 s38, s38, 0x100080
	v_lshl_add_u64 v[216:217], v[218:219], 0, s[16:17]
	s_addc_u32 s39, s39, 0
	s_add_i32 s43, s70, s50
	global_load_lds_dwordx4 v[216:217], off
	v_lshl_add_u64 v[216:217], s[38:39], 0, v[150:151]
	s_mov_b32 m0, s43
	s_nop 0
	global_load_lds_dwordx4 v[216:217], off
	v_lshl_add_u64 v[216:217], s[38:39], 0, v[146:147]
	s_add_i32 m0, s43, 0x2000
	s_nop 0
	global_load_lds_dwordx4 v[216:217], off
	v_lshl_add_u64 v[216:217], v[220:221], 0, s[16:17]
	s_mov_b32 m0, s55
	s_nop 0
	global_load_lds_dwordx4 v[216:217], off
	v_lshl_add_u64 v[216:217], v[222:223], 0, s[16:17]
	s_mov_b32 m0, s56
	s_nop 0
	global_load_lds_dwordx4 v[216:217], off
	s_waitcnt vmcnt(8)
	s_waitcnt lgkmcnt(0)
	s_setprio 1
	s_barrier
	v_mfma_f32_16x16x32_bf16 v[62:65], v[130:133], v[184:187], v[62:65]
	v_mfma_f32_16x16x32_bf16 v[58:61], v[138:141], v[184:187], v[58:61]
	v_mfma_f32_16x16x32_bf16 v[50:53], v[130:133], v[192:195], v[50:53]
	v_mfma_f32_16x16x32_bf16 v[42:45], v[138:141], v[192:195], v[42:45]
	v_mfma_f32_16x16x32_bf16 v[34:37], v[130:133], v[200:203], v[34:37]
	v_mfma_f32_16x16x32_bf16 v[26:29], v[138:141], v[200:203], v[26:29]
	v_mfma_f32_16x16x32_bf16 v[18:21], v[130:133], v[208:211], v[18:21]
	v_mfma_f32_16x16x32_bf16 v[10:13], v[138:141], v[208:211], v[10:13]
	v_mfma_f32_16x16x32_bf16 v[62:65], v[134:137], v[188:191], v[62:65]
	v_mfma_f32_16x16x32_bf16 v[58:61], v[142:145], v[188:191], v[58:61]
	v_mfma_f32_16x16x32_bf16 v[50:53], v[134:137], v[196:199], v[50:53]
	v_mfma_f32_16x16x32_bf16 v[42:45], v[142:145], v[196:199], v[42:45]
	v_mfma_f32_16x16x32_bf16 v[34:37], v[134:137], v[204:207], v[34:37]
	v_mfma_f32_16x16x32_bf16 v[26:29], v[142:145], v[204:207], v[26:29]
	v_mfma_f32_16x16x32_bf16 v[18:21], v[134:137], v[212:215], v[18:21]
	v_mfma_f32_16x16x32_bf16 v[10:13], v[142:145], v[212:215], v[10:13]
	v_mfma_f32_16x16x32_bf16 v[54:57], v[162:165], v[184:187], v[54:57]
	v_mfma_f32_16x16x32_bf16 v[46:49], v[176:179], v[184:187], v[46:49]
	v_mfma_f32_16x16x32_bf16 v[38:41], v[162:165], v[192:195], v[38:41]
	v_mfma_f32_16x16x32_bf16 v[30:33], v[176:179], v[192:195], v[30:33]
	v_mfma_f32_16x16x32_bf16 v[22:25], v[162:165], v[200:203], v[22:25]
	v_mfma_f32_16x16x32_bf16 v[14:17], v[176:179], v[200:203], v[14:17]
	v_mfma_f32_16x16x32_bf16 v[6:9], v[162:165], v[208:211], v[6:9]
	v_mfma_f32_16x16x32_bf16 v[2:5], v[176:179], v[208:211], v[2:5]
	v_mfma_f32_16x16x32_bf16 v[54:57], v[172:175], v[188:191], v[54:57]
	v_mfma_f32_16x16x32_bf16 v[46:49], v[180:183], v[188:191], v[46:49]
	v_mfma_f32_16x16x32_bf16 v[38:41], v[172:175], v[196:199], v[38:41]
	v_mfma_f32_16x16x32_bf16 v[30:33], v[180:183], v[196:199], v[30:33]
	s_barrier
	v_mfma_f32_16x16x32_bf16 v[22:25], v[172:175], v[204:207], v[22:25]
	v_mfma_f32_16x16x32_bf16 v[14:17], v[180:183], v[204:207], v[14:17]
	v_mfma_f32_16x16x32_bf16 v[6:9], v[172:175], v[212:215], v[6:9]
	v_mfma_f32_16x16x32_bf16 v[2:5], v[180:183], v[212:215], v[2:5]
	s_setprio 0
	s_add_i32 s69, s69, 2
	s_add_u32 s2, s2, 0x100
	s_addc_u32 s3, s3, 0
	s_add_u32 s67, s67, 0x100
	s_addc_u32 s68, s68, 0
	s_cmp_gt_u32 s69, 61
	s_cbranch_scc0 .LBB0_1521
	s_and_b64 vcc, exec, s[18:19]
	s_cbranch_vccz .LBB0_1524
	s_barrier

.LBB0_1697:
	ds_read_b128 v[130:133], v238
	ds_read_b128 v[134:137], v238 offset:1024
	ds_read_b128 v[138:141], v238 offset:2048
	ds_read_b128 v[142:145], v238 offset:3072
	ds_read_b128 v[146:149], v239
	ds_read_b128 v[150:153], v239 offset:1024
	ds_read_b128 v[154:157], v239 offset:2048
	ds_read_b128 v[158:161], v239 offset:3072
	s_add_u32 s56, s2, 0x100
	s_addc_u32 s57, s3, 0
	s_cmp_eq_u32 s91, 28
	s_cselect_b32 s61, s49, s57
	s_cselect_b32 s60, s87, s56
	s_cselect_b32 s59, s47, s90
	s_cselect_b32 s58, s88, s89
	v_lshl_add_u64 v[194:195], s[2:3], 0, v[210:211]
	s_add_i32 m0, s55, 0xc000
	ds_read_b128 v[162:165], v240
	ds_read_b128 v[166:169], v240 offset:1024
	ds_read_b128 v[170:173], v240 offset:2048
	ds_read_b128 v[174:177], v240 offset:3072
	ds_read_b128 v[178:181], v240 offset:4096
	ds_read_b128 v[182:185], v240 offset:5120
	ds_read_b128 v[186:189], v240 offset:6144
	ds_read_b128 v[190:193], v240 offset:7168
	global_load_lds_dwordx4 v[194:195], off
	v_lshl_add_u64 v[194:195], s[2:3], 0, v[212:213]
	s_add_i32 m0, s55, 0xe000
	s_nop 0
	global_load_lds_dwordx4 v[194:195], off
	s_waitcnt vmcnt(8)
	s_waitcnt lgkmcnt(0)
	s_setprio 1
	s_barrier
	v_mfma_i32_16x16x64_i8 v[126:129], v[130:133], v[162:165], v[126:129]
	v_mfma_i32_16x16x64_i8 v[122:125], v[138:141], v[162:165], v[122:125]
	v_mfma_i32_16x16x64_i8 v[118:121], v[130:133], v[170:173], v[118:121]
	v_mfma_i32_16x16x64_i8 v[110:113], v[138:141], v[170:173], v[110:113]
	v_mfma_i32_16x16x64_i8 v[78:81], v[130:133], v[178:181], v[78:81]
	v_mfma_i32_16x16x64_i8 v[30:33], v[138:141], v[178:181], v[30:33]
	v_mfma_i32_16x16x64_i8 v[74:77], v[130:133], v[186:189], v[74:77]
	v_mfma_i32_16x16x64_i8 v[26:29], v[138:141], v[186:189], v[26:29]
	v_mfma_i32_16x16x64_i8 v[126:129], v[134:137], v[166:169], v[126:129]
	v_mfma_i32_16x16x64_i8 v[122:125], v[142:145], v[166:169], v[122:125]
	v_mfma_i32_16x16x64_i8 v[118:121], v[134:137], v[174:177], v[118:121]
	v_mfma_i32_16x16x64_i8 v[110:113], v[142:145], v[174:177], v[110:113]
	v_mfma_i32_16x16x64_i8 v[78:81], v[134:137], v[182:185], v[78:81]
	v_mfma_i32_16x16x64_i8 v[30:33], v[142:145], v[182:185], v[30:33]
	v_mfma_i32_16x16x64_i8 v[74:77], v[134:137], v[190:193], v[74:77]
	v_mfma_i32_16x16x64_i8 v[26:29], v[142:145], v[190:193], v[26:29]
	v_mfma_i32_16x16x64_i8 v[102:105], v[146:149], v[162:165], v[102:105]
	v_mfma_i32_16x16x64_i8 v[98:101], v[154:157], v[162:165], v[98:101]
	v_mfma_i32_16x16x64_i8 v[94:97], v[146:149], v[170:173], v[94:97]
	v_mfma_i32_16x16x64_i8 v[90:93], v[154:157], v[170:173], v[90:93]
	v_mfma_i32_16x16x64_i8 v[70:73], v[146:149], v[178:181], v[70:73]
	v_mfma_i32_16x16x64_i8 v[22:25], v[154:157], v[178:181], v[22:25]
	v_mfma_i32_16x16x64_i8 v[66:69], v[146:149], v[186:189], v[66:69]
	v_mfma_i32_16x16x64_i8 v[18:21], v[154:157], v[186:189], v[18:21]
	v_mfma_i32_16x16x64_i8 v[102:105], v[150:153], v[166:169], v[102:105]
	v_mfma_i32_16x16x64_i8 v[98:101], v[158:161], v[166:169], v[98:101]
	v_mfma_i32_16x16x64_i8 v[94:97], v[150:153], v[174:177], v[94:97]
	v_mfma_i32_16x16x64_i8 v[90:93], v[158:161], v[174:177], v[90:93]
	s_barrier
	v_mfma_i32_16x16x64_i8 v[70:73], v[150:153], v[182:185], v[70:73]
	v_mfma_i32_16x16x64_i8 v[22:25], v[158:161], v[182:185], v[22:25]
	v_mfma_i32_16x16x64_i8 v[66:69], v[150:153], v[190:193], v[66:69]
	v_mfma_i32_16x16x64_i8 v[18:21], v[158:161], v[190:193], v[18:21]
	s_setprio 0
	s_add_i32 s2, s83, s66
	v_lshl_add_u64 v[194:195], s[58:59], 0, v[206:207]
	s_mov_b32 m0, s2
	ds_read_b128 v[162:165], v240 offset:16384
	ds_read_b128 v[166:169], v240 offset:17408
	ds_read_b128 v[170:173], v240 offset:18432
	ds_read_b128 v[174:177], v240 offset:19456
	ds_read_b128 v[178:181], v240 offset:20480
	ds_read_b128 v[182:185], v240 offset:21504
	ds_read_b128 v[186:189], v240 offset:22528
	ds_read_b128 v[190:193], v240 offset:23552
	global_load_lds_dwordx4 v[194:195], off
	s_add_i32 m0, s2, 0x2000
	s_add_u32 s2, s58, 0x80000
	v_lshl_add_u64 v[196:197], s[58:59], 0, v[202:203]
	s_addc_u32 s3, s59, 0
	s_add_i32 s43, s84, s66
	global_load_lds_dwordx4 v[196:197], off
	v_lshl_add_u64 v[198:199], s[2:3], 0, v[206:207]
	s_mov_b32 m0, s43
	v_lshl_add_u64 v[200:201], s[60:61], 0, v[204:205]
	global_load_lds_dwordx4 v[198:199], off
	v_lshl_add_u64 v[198:199], s[2:3], 0, v[202:203]
	s_add_i32 m0, s43, 0x2000
	s_nop 0
	global_load_lds_dwordx4 v[198:199], off
	v_lshl_add_u64 v[198:199], s[60:61], 0, v[208:209]
	s_mov_b32 m0, s55
	s_nop 0
	global_load_lds_dwordx4 v[198:199], off
	s_mov_b32 m0, s68
	s_nop 0
	global_load_lds_dwordx4 v[200:201], off
	s_waitcnt vmcnt(8)
	s_waitcnt lgkmcnt(0)
	s_setprio 1
	s_barrier
	v_mfma_i32_16x16x64_i8 v[62:65], v[130:133], v[162:165], v[62:65]
	v_mfma_i32_16x16x64_i8 v[14:17], v[138:141], v[162:165], v[14:17]
	v_mfma_i32_16x16x64_i8 v[58:61], v[130:133], v[170:173], v[58:61]
	v_mfma_i32_16x16x64_i8 v[10:13], v[138:141], v[170:173], v[10:13]
	v_mfma_i32_16x16x64_i8 v[114:117], v[130:133], v[178:181], v[114:117]
	v_mfma_i32_16x16x64_i8 v[106:109], v[138:141], v[178:181], v[106:109]
	v_mfma_i32_16x16x64_i8 v[86:89], v[130:133], v[186:189], v[86:89]
	v_mfma_i32_16x16x64_i8 v[82:85], v[138:141], v[186:189], v[82:85]
	v_mfma_i32_16x16x64_i8 v[62:65], v[134:137], v[166:169], v[62:65]
	v_mfma_i32_16x16x64_i8 v[14:17], v[142:145], v[166:169], v[14:17]
	v_mfma_i32_16x16x64_i8 v[58:61], v[134:137], v[174:177], v[58:61]
	v_mfma_i32_16x16x64_i8 v[10:13], v[142:145], v[174:177], v[10:13]
	v_mfma_i32_16x16x64_i8 v[114:117], v[134:137], v[182:185], v[114:117]
	v_mfma_i32_16x16x64_i8 v[106:109], v[142:145], v[182:185], v[106:109]
	v_mfma_i32_16x16x64_i8 v[86:89], v[134:137], v[190:193], v[86:89]
	v_mfma_i32_16x16x64_i8 v[82:85], v[142:145], v[190:193], v[82:85]
	v_mfma_i32_16x16x64_i8 v[50:53], v[146:149], v[162:165], v[50:53]
	v_mfma_i32_16x16x64_i8 v[6:9], v[154:157], v[162:165], v[6:9]
	v_mfma_i32_16x16x64_i8 v[42:45], v[146:149], v[170:173], v[42:45]
	v_mfma_i32_16x16x64_i8 v[2:5], v[154:157], v[170:173], v[2:5]
	v_mfma_i32_16x16x64_i8 v[54:57], v[146:149], v[178:181], v[54:57]
	v_mfma_i32_16x16x64_i8 v[46:49], v[154:157], v[178:181], v[46:49]
	v_mfma_i32_16x16x64_i8 v[38:41], v[146:149], v[186:189], v[38:41]
	v_mfma_i32_16x16x64_i8 v[34:37], v[154:157], v[186:189], v[34:37]
	v_mfma_i32_16x16x64_i8 v[50:53], v[150:153], v[166:169], v[50:53]
	v_mfma_i32_16x16x64_i8 v[6:9], v[158:161], v[166:169], v[6:9]
	v_mfma_i32_16x16x64_i8 v[42:45], v[150:153], v[174:177], v[42:45]
	v_mfma_i32_16x16x64_i8 v[2:5], v[158:161], v[174:177], v[2:5]
	s_barrier
	v_mfma_i32_16x16x64_i8 v[54:57], v[150:153], v[182:185], v[54:57]
	v_mfma_i32_16x16x64_i8 v[46:49], v[158:161], v[182:185], v[46:49]
	v_mfma_i32_16x16x64_i8 v[38:41], v[150:153], v[190:193], v[38:41]
	v_mfma_i32_16x16x64_i8 v[34:37], v[158:161], v[190:193], v[34:37]
	s_setprio 0
	s_add_i32 s43, 0, 0x18000
	s_add_i32 s92, 0, 0x1c000
	v_add_u32_e32 v142, s43, v237
	v_add_u32_e32 v158, s92, v237
	ds_read_b128 v[130:133], v142
	ds_read_b128 v[134:137], v142 offset:1024
	ds_read_b128 v[138:141], v142 offset:2048
	ds_read_b128 v[142:145], v142 offset:3072
	ds_read_b128 v[146:149], v158
	ds_read_b128 v[150:153], v158 offset:1024
	ds_read_b128 v[154:157], v158 offset:2048
	ds_read_b128 v[158:161], v158 offset:3072
	s_add_u32 s2, s60, 0x4000
	s_addc_u32 s3, s61, 0
	s_mov_b32 m0, s69
	v_lshl_add_u64 v[220:221], s[2:3], 0, v[208:209]
	ds_read_b128 v[162:165], v240 offset:32768
	ds_read_b128 v[166:169], v240 offset:33792
	ds_read_b128 v[170:173], v240 offset:34816
	ds_read_b128 v[174:177], v240 offset:35840
	ds_read_b128 v[178:181], v240 offset:36864
	ds_read_b128 v[182:185], v240 offset:37888
	ds_read_b128 v[186:189], v240 offset:38912
	ds_read_b128 v[190:193], v240 offset:39936
	global_load_lds_dwordx4 v[220:221], off
	v_lshl_add_u64 v[220:221], s[2:3], 0, v[204:205]
	s_mov_b32 m0, s70
	s_nop 0
	global_load_lds_dwordx4 v[220:221], off
	s_waitcnt vmcnt(8)
	s_waitcnt lgkmcnt(0)
	s_setprio 1
	s_barrier
	v_mfma_i32_16x16x64_i8 v[126:129], v[130:133], v[162:165], v[126:129]
	v_mfma_i32_16x16x64_i8 v[122:125], v[138:141], v[162:165], v[122:125]
	v_mfma_i32_16x16x64_i8 v[118:121], v[130:133], v[170:173], v[118:121]
	v_mfma_i32_16x16x64_i8 v[110:113], v[138:141], v[170:173], v[110:113]
	v_mfma_i32_16x16x64_i8 v[78:81], v[130:133], v[178:181], v[78:81]
	v_mfma_i32_16x16x64_i8 v[30:33], v[138:141], v[178:181], v[30:33]
	v_mfma_i32_16x16x64_i8 v[74:77], v[130:133], v[186:189], v[74:77]
	v_mfma_i32_16x16x64_i8 v[26:29], v[138:141], v[186:189], v[26:29]
	v_mfma_i32_16x16x64_i8 v[126:129], v[134:137], v[166:169], v[126:129]
	v_mfma_i32_16x16x64_i8 v[122:125], v[142:145], v[166:169], v[122:125]
	v_mfma_i32_16x16x64_i8 v[118:121], v[134:137], v[174:177], v[118:121]
	v_mfma_i32_16x16x64_i8 v[110:113], v[142:145], v[174:177], v[110:113]
	v_mfma_i32_16x16x64_i8 v[78:81], v[134:137], v[182:185], v[78:81]
	v_mfma_i32_16x16x64_i8 v[30:33], v[142:145], v[182:185], v[30:33]
	v_mfma_i32_16x16x64_i8 v[74:77], v[134:137], v[190:193], v[74:77]
	v_mfma_i32_16x16x64_i8 v[26:29], v[142:145], v[190:193], v[26:29]
	v_mfma_i32_16x16x64_i8 v[102:105], v[146:149], v[162:165], v[102:105]
	v_mfma_i32_16x16x64_i8 v[98:101], v[154:157], v[162:165], v[98:101]
	v_mfma_i32_16x16x64_i8 v[94:97], v[146:149], v[170:173], v[94:97]
	v_mfma_i32_16x16x64_i8 v[90:93], v[154:157], v[170:173], v[90:93]
	v_mfma_i32_16x16x64_i8 v[70:73], v[146:149], v[178:181], v[70:73]
	v_mfma_i32_16x16x64_i8 v[22:25], v[154:157], v[178:181], v[22:25]
	v_mfma_i32_16x16x64_i8 v[66:69], v[146:149], v[186:189], v[66:69]
	v_mfma_i32_16x16x64_i8 v[18:21], v[154:157], v[186:189], v[18:21]
	v_mfma_i32_16x16x64_i8 v[102:105], v[150:153], v[166:169], v[102:105]
	v_mfma_i32_16x16x64_i8 v[98:101], v[158:161], v[166:169], v[98:101]
	v_mfma_i32_16x16x64_i8 v[94:97], v[150:153], v[174:177], v[94:97]
	v_mfma_i32_16x16x64_i8 v[90:93], v[158:161], v[174:177], v[90:93]
	s_barrier
	v_mfma_i32_16x16x64_i8 v[70:73], v[150:153], v[182:185], v[70:73]
	v_mfma_i32_16x16x64_i8 v[22:25], v[158:161], v[182:185], v[22:25]
	v_mfma_i32_16x16x64_i8 v[66:69], v[150:153], v[190:193], v[66:69]
	v_mfma_i32_16x16x64_i8 v[18:21], v[158:161], v[190:193], v[18:21]
	s_setprio 0
	s_add_i32 s2, s43, s66
	v_lshl_add_u64 v[194:195], v[194:195], 0, s[36:37]
	s_mov_b32 m0, s2
	ds_read_b128 v[162:165], v240 offset:49152
	ds_read_b128 v[166:169], v240 offset:50176
	ds_read_b128 v[170:173], v240 offset:51200
	ds_read_b128 v[174:177], v240 offset:52224
	ds_read_b128 v[178:181], v240 offset:53248
	ds_read_b128 v[182:185], v240 offset:54272
	ds_read_b128 v[186:189], v240 offset:55296
	ds_read_b128 v[190:193], v240 offset:56320
	global_load_lds_dwordx4 v[194:195], off
	s_add_i32 m0, s2, 0x2000
	s_add_u32 s2, s58, 0x80080
	v_lshl_add_u64 v[194:195], v[196:197], 0, s[36:37]
	s_addc_u32 s3, s59, 0
	s_add_i32 s43, s92, s66
	global_load_lds_dwordx4 v[194:195], off
	v_lshl_add_u64 v[194:195], s[2:3], 0, v[206:207]
	s_mov_b32 m0, s43
	s_nop 0
	global_load_lds_dwordx4 v[194:195], off
	v_lshl_add_u64 v[194:195], s[2:3], 0, v[202:203]
	s_add_i32 m0, s43, 0x2000
	s_nop 0
	global_load_lds_dwordx4 v[194:195], off
	v_lshl_add_u64 v[194:195], v[198:199], 0, s[36:37]
	s_mov_b32 m0, s77
	s_nop 0
	global_load_lds_dwordx4 v[194:195], off
	v_lshl_add_u64 v[194:195], v[200:201], 0, s[36:37]
	s_mov_b32 m0, s78
	s_nop 0
	global_load_lds_dwordx4 v[194:195], off
	s_waitcnt vmcnt(8)
	s_waitcnt lgkmcnt(0)
	s_setprio 1
	s_barrier
	v_mfma_i32_16x16x64_i8 v[62:65], v[130:133], v[162:165], v[62:65]
	v_mfma_i32_16x16x64_i8 v[14:17], v[138:141], v[162:165], v[14:17]
	v_mfma_i32_16x16x64_i8 v[58:61], v[130:133], v[170:173], v[58:61]
	v_mfma_i32_16x16x64_i8 v[10:13], v[138:141], v[170:173], v[10:13]
	v_mfma_i32_16x16x64_i8 v[114:117], v[130:133], v[178:181], v[114:117]
	v_mfma_i32_16x16x64_i8 v[106:109], v[138:141], v[178:181], v[106:109]
	v_mfma_i32_16x16x64_i8 v[86:89], v[130:133], v[186:189], v[86:89]
	v_mfma_i32_16x16x64_i8 v[82:85], v[138:141], v[186:189], v[82:85]
	v_mfma_i32_16x16x64_i8 v[62:65], v[134:137], v[166:169], v[62:65]
	v_mfma_i32_16x16x64_i8 v[14:17], v[142:145], v[166:169], v[14:17]
	v_mfma_i32_16x16x64_i8 v[58:61], v[134:137], v[174:177], v[58:61]
	v_mfma_i32_16x16x64_i8 v[10:13], v[142:145], v[174:177], v[10:13]
	v_mfma_i32_16x16x64_i8 v[114:117], v[134:137], v[182:185], v[114:117]
	v_mfma_i32_16x16x64_i8 v[106:109], v[142:145], v[182:185], v[106:109]
	v_mfma_i32_16x16x64_i8 v[86:89], v[134:137], v[190:193], v[86:89]
	v_mfma_i32_16x16x64_i8 v[82:85], v[142:145], v[190:193], v[82:85]
	v_mfma_i32_16x16x64_i8 v[50:53], v[146:149], v[162:165], v[50:53]
	v_mfma_i32_16x16x64_i8 v[6:9], v[154:157], v[162:165], v[6:9]
	v_mfma_i32_16x16x64_i8 v[42:45], v[146:149], v[170:173], v[42:45]
	v_mfma_i32_16x16x64_i8 v[2:5], v[154:157], v[170:173], v[2:5]
	v_mfma_i32_16x16x64_i8 v[54:57], v[146:149], v[178:181], v[54:57]
	v_mfma_i32_16x16x64_i8 v[46:49], v[154:157], v[178:181], v[46:49]
	v_mfma_i32_16x16x64_i8 v[38:41], v[146:149], v[186:189], v[38:41]
	v_mfma_i32_16x16x64_i8 v[34:37], v[154:157], v[186:189], v[34:37]
	v_mfma_i32_16x16x64_i8 v[50:53], v[150:153], v[166:169], v[50:53]
	v_mfma_i32_16x16x64_i8 v[6:9], v[158:161], v[166:169], v[6:9]
	v_mfma_i32_16x16x64_i8 v[42:45], v[150:153], v[174:177], v[42:45]
	v_mfma_i32_16x16x64_i8 v[2:5], v[158:161], v[174:177], v[2:5]
	s_barrier
	v_mfma_i32_16x16x64_i8 v[54:57], v[150:153], v[182:185], v[54:57]
	v_mfma_i32_16x16x64_i8 v[46:49], v[158:161], v[182:185], v[46:49]
	v_mfma_i32_16x16x64_i8 v[38:41], v[150:153], v[190:193], v[38:41]
	v_mfma_i32_16x16x64_i8 v[34:37], v[158:161], v[190:193], v[34:37]
	s_setprio 0
	s_add_i32 s91, s91, 2
	s_add_u32 s89, s89, 0x100
	s_addc_u32 s90, s90, 0
	s_cmp_gt_u32 s91, 29
	s_mov_b64 s[2:3], s[56:57]
	s_cbranch_scc0 .LBB0_1697
	s_and_b64 vcc, exec, s[38:39]
	s_cbranch_vccz .LBB0_1700
	s_barrier

.LBB0_1951:
	ds_read_b128 v[130:133], v167
	ds_read_b128 v[134:137], v167 offset:1024
	ds_read_b128 v[138:141], v167 offset:2048
	ds_read_b128 v[142:145], v167 offset:3072
	ds_read_b128 v[170:173], v168
	ds_read_b128 v[174:177], v168 offset:1024
	ds_read_b128 v[178:181], v168 offset:2048
	ds_read_b128 v[182:185], v168 offset:3072
	s_add_u32 s38, s36, 0x100
	s_addc_u32 s39, s37, 0
	s_cmpk_eq_i32 s77, 0x52
	s_cselect_b32 s47, s3, s39
	s_cselect_b32 s46, s2, s38
	s_cselect_b32 s45, s35, s76
	s_cselect_b32 s44, s34, s75
	v_lshl_add_u64 v[162:163], s[36:37], 0, v[154:155]
	s_add_i32 m0, s52, 0xc000
	ds_read_b128 v[186:189], v169
	ds_read_b128 v[190:193], v169 offset:1024
	ds_read_b128 v[194:197], v169 offset:2048
	ds_read_b128 v[198:201], v169 offset:3072
	ds_read_b128 v[202:205], v169 offset:4096
	ds_read_b128 v[206:209], v169 offset:5120
	ds_read_b128 v[210:213], v169 offset:6144
	ds_read_b128 v[214:217], v169 offset:7168
	global_load_lds_dwordx4 v[162:163], off
	v_lshl_add_u64 v[162:163], s[36:37], 0, v[156:157]
	s_add_i32 m0, s52, 0xe000
	s_nop 0
	global_load_lds_dwordx4 v[162:163], off
	s_waitcnt vmcnt(8)
	s_waitcnt lgkmcnt(0)
	s_setprio 1
	s_barrier
	v_mfma_i32_16x16x64_i8 v[126:129], v[130:133], v[186:189], v[126:129]
	v_mfma_i32_16x16x64_i8 v[122:125], v[138:141], v[186:189], v[122:125]
	v_mfma_i32_16x16x64_i8 v[110:113], v[130:133], v[194:197], v[110:113]
	v_mfma_i32_16x16x64_i8 v[106:109], v[138:141], v[194:197], v[106:109]
	v_mfma_i32_16x16x64_i8 v[94:97], v[130:133], v[202:205], v[94:97]
	v_mfma_i32_16x16x64_i8 v[90:93], v[138:141], v[202:205], v[90:93]
	v_mfma_i32_16x16x64_i8 v[78:81], v[130:133], v[210:213], v[78:81]
	v_mfma_i32_16x16x64_i8 v[74:77], v[138:141], v[210:213], v[74:77]
	v_mfma_i32_16x16x64_i8 v[126:129], v[134:137], v[190:193], v[126:129]
	v_mfma_i32_16x16x64_i8 v[122:125], v[142:145], v[190:193], v[122:125]
	v_mfma_i32_16x16x64_i8 v[110:113], v[134:137], v[198:201], v[110:113]
	v_mfma_i32_16x16x64_i8 v[106:109], v[142:145], v[198:201], v[106:109]
	v_mfma_i32_16x16x64_i8 v[94:97], v[134:137], v[206:209], v[94:97]
	v_mfma_i32_16x16x64_i8 v[90:93], v[142:145], v[206:209], v[90:93]
	v_mfma_i32_16x16x64_i8 v[78:81], v[134:137], v[214:217], v[78:81]
	v_mfma_i32_16x16x64_i8 v[74:77], v[142:145], v[214:217], v[74:77]
	v_mfma_i32_16x16x64_i8 v[118:121], v[170:173], v[186:189], v[118:121]
	v_mfma_i32_16x16x64_i8 v[114:117], v[178:181], v[186:189], v[114:117]
	v_mfma_i32_16x16x64_i8 v[102:105], v[170:173], v[194:197], v[102:105]
	v_mfma_i32_16x16x64_i8 v[98:101], v[178:181], v[194:197], v[98:101]
	v_mfma_i32_16x16x64_i8 v[86:89], v[170:173], v[202:205], v[86:89]
	v_mfma_i32_16x16x64_i8 v[82:85], v[178:181], v[202:205], v[82:85]
	v_mfma_i32_16x16x64_i8 v[70:73], v[170:173], v[210:213], v[70:73]
	v_mfma_i32_16x16x64_i8 v[66:69], v[178:181], v[210:213], v[66:69]
	v_mfma_i32_16x16x64_i8 v[118:121], v[174:177], v[190:193], v[118:121]
	v_mfma_i32_16x16x64_i8 v[114:117], v[182:185], v[190:193], v[114:117]
	v_mfma_i32_16x16x64_i8 v[102:105], v[174:177], v[198:201], v[102:105]
	v_mfma_i32_16x16x64_i8 v[98:101], v[182:185], v[198:201], v[98:101]
	s_barrier
	v_mfma_i32_16x16x64_i8 v[86:89], v[174:177], v[206:209], v[86:89]
	v_mfma_i32_16x16x64_i8 v[82:85], v[182:185], v[206:209], v[82:85]
	v_mfma_i32_16x16x64_i8 v[70:73], v[174:177], v[214:217], v[70:73]
	v_mfma_i32_16x16x64_i8 v[66:69], v[182:185], v[214:217], v[66:69]
	s_setprio 0
	s_add_i32 s36, s61, s51
	v_lshl_add_u64 v[162:163], s[44:45], 0, v[150:151]
	s_mov_b32 m0, s36
	ds_read_b128 v[186:189], v169 offset:16384
	ds_read_b128 v[190:193], v169 offset:17408
	ds_read_b128 v[194:197], v169 offset:18432
	ds_read_b128 v[198:201], v169 offset:19456
	ds_read_b128 v[202:205], v169 offset:20480
	ds_read_b128 v[206:209], v169 offset:21504
	ds_read_b128 v[210:213], v169 offset:22528
	ds_read_b128 v[214:217], v169 offset:23552
	global_load_lds_dwordx4 v[162:163], off
	s_add_i32 m0, s36, 0x2000
	s_add_u32 s36, s44, 0x158000
	v_lshl_add_u64 v[218:219], s[44:45], 0, v[146:147]
	s_addc_u32 s37, s45, 0
	s_add_i32 s78, s62, s51
	global_load_lds_dwordx4 v[218:219], off
	v_lshl_add_u64 v[220:221], s[36:37], 0, v[150:151]
	s_mov_b32 m0, s78
	v_lshl_add_u64 v[222:223], s[46:47], 0, v[148:149]
	global_load_lds_dwordx4 v[220:221], off
	v_lshl_add_u64 v[220:221], s[36:37], 0, v[146:147]
	s_add_i32 m0, s78, 0x2000
	s_nop 0
	global_load_lds_dwordx4 v[220:221], off
	v_lshl_add_u64 v[220:221], s[46:47], 0, v[152:153]
	s_mov_b32 m0, s52
	s_nop 0
	global_load_lds_dwordx4 v[220:221], off
	s_mov_b32 m0, s53
	s_nop 0
	global_load_lds_dwordx4 v[222:223], off
	s_waitcnt vmcnt(8)
	s_waitcnt lgkmcnt(0)
	s_setprio 1
	s_barrier
	v_mfma_i32_16x16x64_i8 v[62:65], v[130:133], v[186:189], v[62:65]
	v_mfma_i32_16x16x64_i8 v[58:61], v[138:141], v[186:189], v[58:61]
	v_mfma_i32_16x16x64_i8 v[46:49], v[130:133], v[194:197], v[46:49]
	v_mfma_i32_16x16x64_i8 v[42:45], v[138:141], v[194:197], v[42:45]
	v_mfma_i32_16x16x64_i8 v[30:33], v[130:133], v[202:205], v[30:33]
	v_mfma_i32_16x16x64_i8 v[26:29], v[138:141], v[202:205], v[26:29]
	v_mfma_i32_16x16x64_i8 v[14:17], v[130:133], v[210:213], v[14:17]
	v_mfma_i32_16x16x64_i8 v[10:13], v[138:141], v[210:213], v[10:13]
	v_mfma_i32_16x16x64_i8 v[62:65], v[134:137], v[190:193], v[62:65]
	v_mfma_i32_16x16x64_i8 v[58:61], v[142:145], v[190:193], v[58:61]
	v_mfma_i32_16x16x64_i8 v[46:49], v[134:137], v[198:201], v[46:49]
	v_mfma_i32_16x16x64_i8 v[42:45], v[142:145], v[198:201], v[42:45]
	v_mfma_i32_16x16x64_i8 v[30:33], v[134:137], v[206:209], v[30:33]
	v_mfma_i32_16x16x64_i8 v[26:29], v[142:145], v[206:209], v[26:29]
	v_mfma_i32_16x16x64_i8 v[14:17], v[134:137], v[214:217], v[14:17]
	v_mfma_i32_16x16x64_i8 v[10:13], v[142:145], v[214:217], v[10:13]
	v_mfma_i32_16x16x64_i8 v[54:57], v[170:173], v[186:189], v[54:57]
	v_mfma_i32_16x16x64_i8 v[50:53], v[178:181], v[186:189], v[50:53]
	v_mfma_i32_16x16x64_i8 v[38:41], v[170:173], v[194:197], v[38:41]
	v_mfma_i32_16x16x64_i8 v[34:37], v[178:181], v[194:197], v[34:37]
	v_mfma_i32_16x16x64_i8 v[22:25], v[170:173], v[202:205], v[22:25]
	v_mfma_i32_16x16x64_i8 v[18:21], v[178:181], v[202:205], v[18:21]
	v_mfma_i32_16x16x64_i8 v[6:9], v[170:173], v[210:213], v[6:9]
	v_mfma_i32_16x16x64_i8 v[2:5], v[178:181], v[210:213], v[2:5]
	v_mfma_i32_16x16x64_i8 v[54:57], v[174:177], v[190:193], v[54:57]
	v_mfma_i32_16x16x64_i8 v[50:53], v[182:185], v[190:193], v[50:53]
	v_mfma_i32_16x16x64_i8 v[38:41], v[174:177], v[198:201], v[38:41]
	v_mfma_i32_16x16x64_i8 v[34:37], v[182:185], v[198:201], v[34:37]
	s_barrier
	v_mfma_i32_16x16x64_i8 v[22:25], v[174:177], v[206:209], v[22:25]
	v_mfma_i32_16x16x64_i8 v[18:21], v[182:185], v[206:209], v[18:21]
	v_mfma_i32_16x16x64_i8 v[6:9], v[174:177], v[214:217], v[6:9]
	v_mfma_i32_16x16x64_i8 v[2:5], v[182:185], v[214:217], v[2:5]
	s_setprio 0
	s_add_i32 s78, 0, 0x18000
	s_add_i32 s79, 0, 0x1c000
	v_add_u32_e32 v142, s78, v166
	v_add_u32_e32 v182, s79, v166
	ds_read_b128 v[130:133], v142
	ds_read_b128 v[134:137], v142 offset:1024
	ds_read_b128 v[138:141], v142 offset:2048
	ds_read_b128 v[142:145], v142 offset:3072
	ds_read_b128 v[170:173], v182
	ds_read_b128 v[174:177], v182 offset:1024
	ds_read_b128 v[178:181], v182 offset:2048
	ds_read_b128 v[182:185], v182 offset:3072
	s_add_u32 s36, s46, 0x158000
	s_addc_u32 s37, s47, 0
	s_mov_b32 m0, s54
	v_lshl_add_u64 v[224:225], s[36:37], 0, v[152:153]
	ds_read_b128 v[186:189], v169 offset:32768
	ds_read_b128 v[190:193], v169 offset:33792
	ds_read_b128 v[194:197], v169 offset:34816
	ds_read_b128 v[198:201], v169 offset:35840
	ds_read_b128 v[202:205], v169 offset:36864
	ds_read_b128 v[206:209], v169 offset:37888
	ds_read_b128 v[210:213], v169 offset:38912
	ds_read_b128 v[214:217], v169 offset:39936
	global_load_lds_dwordx4 v[224:225], off
	v_lshl_add_u64 v[224:225], s[36:37], 0, v[148:149]
	s_mov_b32 m0, s55
	s_nop 0
	global_load_lds_dwordx4 v[224:225], off
	s_waitcnt vmcnt(8)
	s_waitcnt lgkmcnt(0)
	s_setprio 1
	s_barrier
	v_mfma_i32_16x16x64_i8 v[126:129], v[130:133], v[186:189], v[126:129]
	v_mfma_i32_16x16x64_i8 v[122:125], v[138:141], v[186:189], v[122:125]
	v_mfma_i32_16x16x64_i8 v[110:113], v[130:133], v[194:197], v[110:113]
	v_mfma_i32_16x16x64_i8 v[106:109], v[138:141], v[194:197], v[106:109]
	v_mfma_i32_16x16x64_i8 v[94:97], v[130:133], v[202:205], v[94:97]
	v_mfma_i32_16x16x64_i8 v[90:93], v[138:141], v[202:205], v[90:93]
	v_mfma_i32_16x16x64_i8 v[78:81], v[130:133], v[210:213], v[78:81]
	v_mfma_i32_16x16x64_i8 v[74:77], v[138:141], v[210:213], v[74:77]
	v_mfma_i32_16x16x64_i8 v[126:129], v[134:137], v[190:193], v[126:129]
	v_mfma_i32_16x16x64_i8 v[122:125], v[142:145], v[190:193], v[122:125]
	v_mfma_i32_16x16x64_i8 v[110:113], v[134:137], v[198:201], v[110:113]
	v_mfma_i32_16x16x64_i8 v[106:109], v[142:145], v[198:201], v[106:109]
	v_mfma_i32_16x16x64_i8 v[94:97], v[134:137], v[206:209], v[94:97]
	v_mfma_i32_16x16x64_i8 v[90:93], v[142:145], v[206:209], v[90:93]
	v_mfma_i32_16x16x64_i8 v[78:81], v[134:137], v[214:217], v[78:81]
	v_mfma_i32_16x16x64_i8 v[74:77], v[142:145], v[214:217], v[74:77]
	v_mfma_i32_16x16x64_i8 v[118:121], v[170:173], v[186:189], v[118:121]
	v_mfma_i32_16x16x64_i8 v[114:117], v[178:181], v[186:189], v[114:117]
	v_mfma_i32_16x16x64_i8 v[102:105], v[170:173], v[194:197], v[102:105]
	v_mfma_i32_16x16x64_i8 v[98:101], v[178:181], v[194:197], v[98:101]
	v_mfma_i32_16x16x64_i8 v[86:89], v[170:173], v[202:205], v[86:89]
	v_mfma_i32_16x16x64_i8 v[82:85], v[178:181], v[202:205], v[82:85]
	v_mfma_i32_16x16x64_i8 v[70:73], v[170:173], v[210:213], v[70:73]
	v_mfma_i32_16x16x64_i8 v[66:69], v[178:181], v[210:213], v[66:69]
	v_mfma_i32_16x16x64_i8 v[118:121], v[174:177], v[190:193], v[118:121]
	v_mfma_i32_16x16x64_i8 v[114:117], v[182:185], v[190:193], v[114:117]
	v_mfma_i32_16x16x64_i8 v[102:105], v[174:177], v[198:201], v[102:105]
	v_mfma_i32_16x16x64_i8 v[98:101], v[182:185], v[198:201], v[98:101]
	s_barrier
	v_mfma_i32_16x16x64_i8 v[86:89], v[174:177], v[206:209], v[86:89]
	v_mfma_i32_16x16x64_i8 v[82:85], v[182:185], v[206:209], v[82:85]
	v_mfma_i32_16x16x64_i8 v[70:73], v[174:177], v[214:217], v[70:73]
	v_mfma_i32_16x16x64_i8 v[66:69], v[182:185], v[214:217], v[66:69]
	s_setprio 0
	s_add_i32 s36, s78, s51
	v_lshl_add_u64 v[162:163], v[162:163], 0, s[14:15]
	s_mov_b32 m0, s36
	ds_read_b128 v[186:189], v169 offset:49152
	ds_read_b128 v[190:193], v169 offset:50176
	ds_read_b128 v[194:197], v169 offset:51200
	ds_read_b128 v[198:201], v169 offset:52224
	ds_read_b128 v[202:205], v169 offset:53248
	ds_read_b128 v[206:209], v169 offset:54272
	ds_read_b128 v[210:213], v169 offset:55296
	ds_read_b128 v[214:217], v169 offset:56320
	global_load_lds_dwordx4 v[162:163], off
	s_add_i32 m0, s36, 0x2000
	s_add_u32 s36, s44, 0x158080
	v_lshl_add_u64 v[162:163], v[218:219], 0, s[14:15]
	s_addc_u32 s37, s45, 0
	s_add_i32 s44, s79, s51
	global_load_lds_dwordx4 v[162:163], off
	v_lshl_add_u64 v[162:163], s[36:37], 0, v[150:151]
	s_mov_b32 m0, s44
	s_nop 0
	global_load_lds_dwordx4 v[162:163], off
	v_lshl_add_u64 v[162:163], s[36:37], 0, v[146:147]
	s_add_i32 m0, s44, 0x2000
	s_nop 0
	global_load_lds_dwordx4 v[162:163], off
	v_lshl_add_u64 v[162:163], v[220:221], 0, s[14:15]
	s_mov_b32 m0, s59
	s_nop 0
	global_load_lds_dwordx4 v[162:163], off
	v_lshl_add_u64 v[162:163], v[222:223], 0, s[14:15]
	s_mov_b32 m0, s60
	s_nop 0
	global_load_lds_dwordx4 v[162:163], off
	s_waitcnt vmcnt(8)
	s_waitcnt lgkmcnt(0)
	s_setprio 1
	s_barrier
	v_mfma_i32_16x16x64_i8 v[62:65], v[130:133], v[186:189], v[62:65]
	v_mfma_i32_16x16x64_i8 v[58:61], v[138:141], v[186:189], v[58:61]
	v_mfma_i32_16x16x64_i8 v[46:49], v[130:133], v[194:197], v[46:49]
	v_mfma_i32_16x16x64_i8 v[42:45], v[138:141], v[194:197], v[42:45]
	v_mfma_i32_16x16x64_i8 v[30:33], v[130:133], v[202:205], v[30:33]
	v_mfma_i32_16x16x64_i8 v[26:29], v[138:141], v[202:205], v[26:29]
	v_mfma_i32_16x16x64_i8 v[14:17], v[130:133], v[210:213], v[14:17]
	v_mfma_i32_16x16x64_i8 v[10:13], v[138:141], v[210:213], v[10:13]
	v_mfma_i32_16x16x64_i8 v[62:65], v[134:137], v[190:193], v[62:65]
	v_mfma_i32_16x16x64_i8 v[58:61], v[142:145], v[190:193], v[58:61]
	v_mfma_i32_16x16x64_i8 v[46:49], v[134:137], v[198:201], v[46:49]
	v_mfma_i32_16x16x64_i8 v[42:45], v[142:145], v[198:201], v[42:45]
	v_mfma_i32_16x16x64_i8 v[30:33], v[134:137], v[206:209], v[30:33]
	v_mfma_i32_16x16x64_i8 v[26:29], v[142:145], v[206:209], v[26:29]
	v_mfma_i32_16x16x64_i8 v[14:17], v[134:137], v[214:217], v[14:17]
	v_mfma_i32_16x16x64_i8 v[10:13], v[142:145], v[214:217], v[10:13]
	v_mfma_i32_16x16x64_i8 v[54:57], v[170:173], v[186:189], v[54:57]
	v_mfma_i32_16x16x64_i8 v[50:53], v[178:181], v[186:189], v[50:53]
	v_mfma_i32_16x16x64_i8 v[38:41], v[170:173], v[194:197], v[38:41]
	v_mfma_i32_16x16x64_i8 v[34:37], v[178:181], v[194:197], v[34:37]
	v_mfma_i32_16x16x64_i8 v[22:25], v[170:173], v[202:205], v[22:25]
	v_mfma_i32_16x16x64_i8 v[18:21], v[178:181], v[202:205], v[18:21]
	v_mfma_i32_16x16x64_i8 v[6:9], v[170:173], v[210:213], v[6:9]
	v_mfma_i32_16x16x64_i8 v[2:5], v[178:181], v[210:213], v[2:5]
	v_mfma_i32_16x16x64_i8 v[54:57], v[174:177], v[190:193], v[54:57]
	v_mfma_i32_16x16x64_i8 v[50:53], v[182:185], v[190:193], v[50:53]
	v_mfma_i32_16x16x64_i8 v[38:41], v[174:177], v[198:201], v[38:41]
	v_mfma_i32_16x16x64_i8 v[34:37], v[182:185], v[198:201], v[34:37]
	s_barrier
	v_mfma_i32_16x16x64_i8 v[22:25], v[174:177], v[206:209], v[22:25]
	v_mfma_i32_16x16x64_i8 v[18:21], v[182:185], v[206:209], v[18:21]
	v_mfma_i32_16x16x64_i8 v[6:9], v[174:177], v[214:217], v[6:9]
	v_mfma_i32_16x16x64_i8 v[2:5], v[182:185], v[214:217], v[2:5]
	s_setprio 0
	s_add_i32 s77, s77, 2
	s_add_u32 s75, s75, 0x100
	s_addc_u32 s76, s76, 0
	s_cmpk_gt_u32 s77, 0x53
	s_mov_b64 s[36:37], s[38:39]
	s_cbranch_scc0 .LBB0_1951
	s_and_b64 vcc, exec, s[16:17]
	s_cbranch_vccz .LBB0_1954
	s_barrier
